# v12 + SP1 load segments: the two LDS-DMA pieces issued after the first 8 ds_reads, A-fragment reads behind them
# speedup vs baseline: 1.0033x; 1.0033x over previous
.LBB0_121:
	ds_read_b128 v[164:167], v131
	ds_read_b128 v[168:171], v131 offset:1024
	ds_read_b128 v[172:175], v131 offset:2048
	ds_read_b128 v[176:179], v131 offset:3072
	ds_read_b128 v[180:183], v160
	ds_read_b128 v[184:187], v160 offset:1024
	ds_read_b128 v[188:191], v160 offset:2048
	ds_read_b128 v[192:195], v160 offset:3072
	s_add_i32 s55, s52, 0xfffc0080
	s_cmp_eq_u32 s54, 12
	s_cselect_b32 s57, s16, s55
	s_cselect_b32 s56, s17, s53
	s_or_b32 s55, s57, 0x80
	s_mov_b32 m0, s40
	s_nop 0
	buffer_load_dwordx4 v156, s[12:15], s52 offen lds
	s_nop 0
	s_mov_b32 m0, s41
	s_nop 0
	buffer_load_dwordx4 v157, s[12:15], s52 offen lds
	ds_read_b128 v[196:199], v161
	ds_read_b128 v[200:203], v161 offset:1024
	ds_read_b128 v[204:207], v161 offset:2048
	ds_read_b128 v[208:211], v161 offset:3072
	ds_read_b128 v[212:215], v161 offset:4096
	ds_read_b128 v[216:219], v161 offset:5120
	ds_read_b128 v[220:223], v161 offset:6144
	ds_read_b128 v[224:227], v161 offset:7168
	s_waitcnt vmcnt(8)
	s_waitcnt lgkmcnt(0)
	s_barrier
	s_setprio 1
	s_waitcnt lgkmcnt(7)
	v_mfma_f32_16x16x32_bf16 v[126:129], v[164:167], v[196:199], v[126:129]
	v_mfma_f32_16x16x32_bf16 v[122:125], v[172:175], v[196:199], v[122:125]
	s_waitcnt lgkmcnt(5)
	v_mfma_f32_16x16x32_bf16 v[118:121], v[164:167], v[204:207], v[118:121]
	v_mfma_f32_16x16x32_bf16 v[110:113], v[172:175], v[204:207], v[110:113]
	s_waitcnt lgkmcnt(3)
	v_mfma_f32_16x16x32_bf16 v[102:105], v[164:167], v[212:215], v[102:105]
	v_mfma_f32_16x16x32_bf16 v[94:97], v[172:175], v[212:215], v[94:97]
	s_waitcnt lgkmcnt(1)
	v_mfma_f32_16x16x32_bf16 v[86:89], v[164:167], v[220:223], v[86:89]
	v_mfma_f32_16x16x32_bf16 v[78:81], v[172:175], v[220:223], v[78:81]
	v_mfma_f32_16x16x32_bf16 v[126:129], v[168:171], v[200:203], v[126:129]
	v_mfma_f32_16x16x32_bf16 v[122:125], v[176:179], v[200:203], v[122:125]
	v_mfma_f32_16x16x32_bf16 v[118:121], v[168:171], v[208:211], v[118:121]
	v_mfma_f32_16x16x32_bf16 v[110:113], v[176:179], v[208:211], v[110:113]
	v_mfma_f32_16x16x32_bf16 v[102:105], v[168:171], v[216:219], v[102:105]
	v_mfma_f32_16x16x32_bf16 v[94:97], v[176:179], v[216:219], v[94:97]
	s_waitcnt lgkmcnt(0)
	v_mfma_f32_16x16x32_bf16 v[86:89], v[168:171], v[224:227], v[86:89]
	v_mfma_f32_16x16x32_bf16 v[78:81], v[176:179], v[224:227], v[78:81]
	s_setprio 0
	s_setprio 1
	v_mfma_f32_16x16x32_bf16 v[114:117], v[180:183], v[196:199], v[114:117]
	v_mfma_f32_16x16x32_bf16 v[106:109], v[188:191], v[196:199], v[106:109]
	v_mfma_f32_16x16x32_bf16 v[98:101], v[180:183], v[204:207], v[98:101]
	v_mfma_f32_16x16x32_bf16 v[90:93], v[188:191], v[204:207], v[90:93]
	v_mfma_f32_16x16x32_bf16 v[82:85], v[180:183], v[212:215], v[82:85]
	v_mfma_f32_16x16x32_bf16 v[74:77], v[188:191], v[212:215], v[74:77]
	v_mfma_f32_16x16x32_bf16 v[70:73], v[180:183], v[220:223], v[70:73]
	v_mfma_f32_16x16x32_bf16 v[66:69], v[188:191], v[220:223], v[66:69]
	v_mfma_f32_16x16x32_bf16 v[114:117], v[184:187], v[200:203], v[114:117]
	v_mfma_f32_16x16x32_bf16 v[106:109], v[192:195], v[200:203], v[106:109]
	v_mfma_f32_16x16x32_bf16 v[98:101], v[184:187], v[208:211], v[98:101]
	v_mfma_f32_16x16x32_bf16 v[90:93], v[192:195], v[208:211], v[90:93]
	v_mfma_f32_16x16x32_bf16 v[82:85], v[184:187], v[216:219], v[82:85]
	v_mfma_f32_16x16x32_bf16 v[74:77], v[192:195], v[216:219], v[74:77]
	v_mfma_f32_16x16x32_bf16 v[70:73], v[184:187], v[224:227], v[70:73]
	v_mfma_f32_16x16x32_bf16 v[66:69], v[192:195], v[224:227], v[66:69]
	s_setprio 0
	s_barrier
	ds_read_b128 v[196:199], v161 offset:16384
	ds_read_b128 v[200:203], v161 offset:17408
	s_mov_b32 m0, s22
	s_nop 0
	buffer_load_dwordx4 v154, s[8:11], s56 offen lds
	ds_read_b128 v[204:207], v161 offset:18432
	ds_read_b128 v[208:211], v161 offset:19456
	s_add_i32 s58, s56, 0x40000
	s_mov_b32 m0, s23
	s_nop 0
	buffer_load_dwordx4 v155, s[8:11], s56 offen lds
	ds_read_b128 v[212:215], v161 offset:20480
	ds_read_b128 v[216:219], v161 offset:21504
	s_nop 0
	s_mov_b32 m0, s24
	s_nop 0
	buffer_load_dwordx4 v154, s[8:11], s58 offen lds
	ds_read_b128 v[220:223], v161 offset:22528
	ds_read_b128 v[224:227], v161 offset:23552
	s_nop 0
	s_mov_b32 m0, s25
	s_nop 0
	buffer_load_dwordx4 v155, s[8:11], s58 offen lds
	s_nop 0
	s_mov_b32 m0, s21
	s_nop 0
	buffer_load_dwordx4 v156, s[12:15], s57 offen lds
	s_nop 0
	s_mov_b32 m0, s27
	s_nop 0
	buffer_load_dwordx4 v157, s[12:15], s57 offen lds
	s_waitcnt vmcnt(8)
	s_waitcnt lgkmcnt(0)
	s_barrier
	s_setprio 1
	s_waitcnt lgkmcnt(7)
	v_mfma_f32_16x16x32_bf16 v[62:65], v[164:167], v[196:199], v[62:65]
	v_mfma_f32_16x16x32_bf16 v[58:61], v[172:175], v[196:199], v[58:61]
	s_waitcnt lgkmcnt(5)
	v_mfma_f32_16x16x32_bf16 v[54:57], v[164:167], v[204:207], v[54:57]
	v_mfma_f32_16x16x32_bf16 v[46:49], v[172:175], v[204:207], v[46:49]
	s_waitcnt lgkmcnt(3)
	v_mfma_f32_16x16x32_bf16 v[38:41], v[164:167], v[212:215], v[38:41]
	v_mfma_f32_16x16x32_bf16 v[30:33], v[172:175], v[212:215], v[30:33]
	s_waitcnt lgkmcnt(1)
	v_mfma_f32_16x16x32_bf16 v[22:25], v[164:167], v[220:223], v[22:25]
	v_mfma_f32_16x16x32_bf16 v[14:17], v[172:175], v[220:223], v[14:17]
	v_mfma_f32_16x16x32_bf16 v[62:65], v[168:171], v[200:203], v[62:65]
	v_mfma_f32_16x16x32_bf16 v[58:61], v[176:179], v[200:203], v[58:61]
	v_mfma_f32_16x16x32_bf16 v[54:57], v[168:171], v[208:211], v[54:57]
	v_mfma_f32_16x16x32_bf16 v[46:49], v[176:179], v[208:211], v[46:49]
	v_mfma_f32_16x16x32_bf16 v[38:41], v[168:171], v[216:219], v[38:41]
	v_mfma_f32_16x16x32_bf16 v[30:33], v[176:179], v[216:219], v[30:33]
	s_waitcnt lgkmcnt(0)
	v_mfma_f32_16x16x32_bf16 v[22:25], v[168:171], v[224:227], v[22:25]
	v_mfma_f32_16x16x32_bf16 v[14:17], v[176:179], v[224:227], v[14:17]
	s_setprio 0
	s_setprio 1
	v_mfma_f32_16x16x32_bf16 v[50:53], v[180:183], v[196:199], v[50:53]
	v_mfma_f32_16x16x32_bf16 v[42:45], v[188:191], v[196:199], v[42:45]
	v_mfma_f32_16x16x32_bf16 v[34:37], v[180:183], v[204:207], v[34:37]
	v_mfma_f32_16x16x32_bf16 v[26:29], v[188:191], v[204:207], v[26:29]
	v_mfma_f32_16x16x32_bf16 v[18:21], v[180:183], v[212:215], v[18:21]
	v_mfma_f32_16x16x32_bf16 v[10:13], v[188:191], v[212:215], v[10:13]
	v_mfma_f32_16x16x32_bf16 v[6:9], v[180:183], v[220:223], v[6:9]
	v_mfma_f32_16x16x32_bf16 v[2:5], v[188:191], v[220:223], v[2:5]
	v_mfma_f32_16x16x32_bf16 v[50:53], v[184:187], v[200:203], v[50:53]
	v_mfma_f32_16x16x32_bf16 v[42:45], v[192:195], v[200:203], v[42:45]
	v_mfma_f32_16x16x32_bf16 v[34:37], v[184:187], v[208:211], v[34:37]
	v_mfma_f32_16x16x32_bf16 v[26:29], v[192:195], v[208:211], v[26:29]
	v_mfma_f32_16x16x32_bf16 v[18:21], v[184:187], v[216:219], v[18:21]
	v_mfma_f32_16x16x32_bf16 v[10:13], v[192:195], v[216:219], v[10:13]
	v_mfma_f32_16x16x32_bf16 v[6:9], v[184:187], v[224:227], v[6:9]
	v_mfma_f32_16x16x32_bf16 v[2:5], v[192:195], v[224:227], v[2:5]
	s_setprio 0
	s_barrier
	ds_read_b128 v[164:167], v162
	ds_read_b128 v[168:171], v162 offset:1024
	ds_read_b128 v[172:175], v162 offset:2048
	ds_read_b128 v[176:179], v162 offset:3072
	ds_read_b128 v[180:183], v163
	ds_read_b128 v[184:187], v163 offset:1024
	ds_read_b128 v[188:191], v163 offset:2048
	ds_read_b128 v[192:195], v163 offset:3072
	s_add_i32 s57, s57, 0x40000
	s_mov_b32 m0, s28
	s_nop 0
	buffer_load_dwordx4 v156, s[12:15], s57 offen lds
	s_nop 0
	s_mov_b32 m0, s30
	s_nop 0
	buffer_load_dwordx4 v157, s[12:15], s57 offen lds
	ds_read_b128 v[196:199], v161 offset:32768
	ds_read_b128 v[200:203], v161 offset:33792
	ds_read_b128 v[204:207], v161 offset:34816
	ds_read_b128 v[208:211], v161 offset:35840
	ds_read_b128 v[212:215], v161 offset:36864
	ds_read_b128 v[216:219], v161 offset:37888
	ds_read_b128 v[220:223], v161 offset:38912
	ds_read_b128 v[224:227], v161 offset:39936
	s_waitcnt vmcnt(8)
	s_waitcnt lgkmcnt(0)
	s_barrier
	s_setprio 1
	s_waitcnt lgkmcnt(7)
	v_mfma_f32_16x16x32_bf16 v[126:129], v[164:167], v[196:199], v[126:129]
	v_mfma_f32_16x16x32_bf16 v[122:125], v[172:175], v[196:199], v[122:125]
	s_waitcnt lgkmcnt(5)
	v_mfma_f32_16x16x32_bf16 v[118:121], v[164:167], v[204:207], v[118:121]
	v_mfma_f32_16x16x32_bf16 v[110:113], v[172:175], v[204:207], v[110:113]
	s_waitcnt lgkmcnt(3)
	v_mfma_f32_16x16x32_bf16 v[102:105], v[164:167], v[212:215], v[102:105]
	v_mfma_f32_16x16x32_bf16 v[94:97], v[172:175], v[212:215], v[94:97]
	s_waitcnt lgkmcnt(1)
	v_mfma_f32_16x16x32_bf16 v[86:89], v[164:167], v[220:223], v[86:89]
	v_mfma_f32_16x16x32_bf16 v[78:81], v[172:175], v[220:223], v[78:81]
	v_mfma_f32_16x16x32_bf16 v[126:129], v[168:171], v[200:203], v[126:129]
	v_mfma_f32_16x16x32_bf16 v[122:125], v[176:179], v[200:203], v[122:125]
	v_mfma_f32_16x16x32_bf16 v[118:121], v[168:171], v[208:211], v[118:121]
	v_mfma_f32_16x16x32_bf16 v[110:113], v[176:179], v[208:211], v[110:113]
	v_mfma_f32_16x16x32_bf16 v[102:105], v[168:171], v[216:219], v[102:105]
	v_mfma_f32_16x16x32_bf16 v[94:97], v[176:179], v[216:219], v[94:97]
	s_waitcnt lgkmcnt(0)
	v_mfma_f32_16x16x32_bf16 v[86:89], v[168:171], v[224:227], v[86:89]
	v_mfma_f32_16x16x32_bf16 v[78:81], v[176:179], v[224:227], v[78:81]
	s_setprio 0
	s_setprio 1
	v_mfma_f32_16x16x32_bf16 v[114:117], v[180:183], v[196:199], v[114:117]
	v_mfma_f32_16x16x32_bf16 v[106:109], v[188:191], v[196:199], v[106:109]
	v_mfma_f32_16x16x32_bf16 v[98:101], v[180:183], v[204:207], v[98:101]
	v_mfma_f32_16x16x32_bf16 v[90:93], v[188:191], v[204:207], v[90:93]
	v_mfma_f32_16x16x32_bf16 v[82:85], v[180:183], v[212:215], v[82:85]
	v_mfma_f32_16x16x32_bf16 v[74:77], v[188:191], v[212:215], v[74:77]
	v_mfma_f32_16x16x32_bf16 v[70:73], v[180:183], v[220:223], v[70:73]
	v_mfma_f32_16x16x32_bf16 v[66:69], v[188:191], v[220:223], v[66:69]
	v_mfma_f32_16x16x32_bf16 v[114:117], v[184:187], v[200:203], v[114:117]
	v_mfma_f32_16x16x32_bf16 v[106:109], v[192:195], v[200:203], v[106:109]
	v_mfma_f32_16x16x32_bf16 v[98:101], v[184:187], v[208:211], v[98:101]
	v_mfma_f32_16x16x32_bf16 v[90:93], v[192:195], v[208:211], v[90:93]
	v_mfma_f32_16x16x32_bf16 v[82:85], v[184:187], v[216:219], v[82:85]
	v_mfma_f32_16x16x32_bf16 v[74:77], v[192:195], v[216:219], v[74:77]
	v_mfma_f32_16x16x32_bf16 v[70:73], v[184:187], v[224:227], v[70:73]
	v_mfma_f32_16x16x32_bf16 v[66:69], v[192:195], v[224:227], v[66:69]
	s_setprio 0
	s_barrier
	ds_read_b128 v[196:199], v161 offset:49152
	ds_read_b128 v[200:203], v161 offset:50176
	s_or_b32 s57, s56, 0x80
	s_mov_b32 m0, s34
	s_nop 0
	buffer_load_dwordx4 v154, s[8:11], s57 offen lds
	ds_read_b128 v[204:207], v161 offset:51200
	ds_read_b128 v[208:211], v161 offset:52224
	s_add_i32 s56, s56, 0x40080
	s_mov_b32 m0, s35
	s_nop 0
	buffer_load_dwordx4 v155, s[8:11], s57 offen lds
	ds_read_b128 v[212:215], v161 offset:53248
	ds_read_b128 v[216:219], v161 offset:54272
	s_nop 0
	s_mov_b32 m0, s38
	s_nop 0
	buffer_load_dwordx4 v154, s[8:11], s56 offen lds
	ds_read_b128 v[220:223], v161 offset:55296
	ds_read_b128 v[224:227], v161 offset:56320
	s_nop 0
	s_mov_b32 m0, s39
	s_nop 0
	buffer_load_dwordx4 v155, s[8:11], s56 offen lds
	s_nop 0
	s_mov_b32 m0, s36
	s_nop 0
	buffer_load_dwordx4 v156, s[12:15], s55 offen lds
	s_nop 0
	s_mov_b32 m0, s37
	s_nop 0
	buffer_load_dwordx4 v157, s[12:15], s55 offen lds
	s_waitcnt vmcnt(8)
	s_waitcnt lgkmcnt(0)
	s_barrier
	s_setprio 1
	s_waitcnt lgkmcnt(7)
	v_mfma_f32_16x16x32_bf16 v[62:65], v[164:167], v[196:199], v[62:65]
	v_mfma_f32_16x16x32_bf16 v[58:61], v[172:175], v[196:199], v[58:61]
	s_waitcnt lgkmcnt(5)
	v_mfma_f32_16x16x32_bf16 v[54:57], v[164:167], v[204:207], v[54:57]
	v_mfma_f32_16x16x32_bf16 v[46:49], v[172:175], v[204:207], v[46:49]
	s_waitcnt lgkmcnt(3)
	v_mfma_f32_16x16x32_bf16 v[38:41], v[164:167], v[212:215], v[38:41]
	v_mfma_f32_16x16x32_bf16 v[30:33], v[172:175], v[212:215], v[30:33]
	s_waitcnt lgkmcnt(1)
	v_mfma_f32_16x16x32_bf16 v[22:25], v[164:167], v[220:223], v[22:25]
	v_mfma_f32_16x16x32_bf16 v[14:17], v[172:175], v[220:223], v[14:17]
	v_mfma_f32_16x16x32_bf16 v[62:65], v[168:171], v[200:203], v[62:65]
	v_mfma_f32_16x16x32_bf16 v[58:61], v[176:179], v[200:203], v[58:61]
	v_mfma_f32_16x16x32_bf16 v[54:57], v[168:171], v[208:211], v[54:57]
	v_mfma_f32_16x16x32_bf16 v[46:49], v[176:179], v[208:211], v[46:49]
	v_mfma_f32_16x16x32_bf16 v[38:41], v[168:171], v[216:219], v[38:41]
	v_mfma_f32_16x16x32_bf16 v[30:33], v[176:179], v[216:219], v[30:33]
	s_waitcnt lgkmcnt(0)
	v_mfma_f32_16x16x32_bf16 v[22:25], v[168:171], v[224:227], v[22:25]
	v_mfma_f32_16x16x32_bf16 v[14:17], v[176:179], v[224:227], v[14:17]
	s_setprio 0
	s_setprio 1
	v_mfma_f32_16x16x32_bf16 v[50:53], v[180:183], v[196:199], v[50:53]
	v_mfma_f32_16x16x32_bf16 v[42:45], v[188:191], v[196:199], v[42:45]
	v_mfma_f32_16x16x32_bf16 v[34:37], v[180:183], v[204:207], v[34:37]
	v_mfma_f32_16x16x32_bf16 v[26:29], v[188:191], v[204:207], v[26:29]
	v_mfma_f32_16x16x32_bf16 v[18:21], v[180:183], v[212:215], v[18:21]
	v_mfma_f32_16x16x32_bf16 v[10:13], v[188:191], v[212:215], v[10:13]
	v_mfma_f32_16x16x32_bf16 v[6:9], v[180:183], v[220:223], v[6:9]
	v_mfma_f32_16x16x32_bf16 v[2:5], v[188:191], v[220:223], v[2:5]
	v_mfma_f32_16x16x32_bf16 v[50:53], v[184:187], v[200:203], v[50:53]
	v_mfma_f32_16x16x32_bf16 v[42:45], v[192:195], v[200:203], v[42:45]
	v_mfma_f32_16x16x32_bf16 v[34:37], v[184:187], v[208:211], v[34:37]
	v_mfma_f32_16x16x32_bf16 v[26:29], v[192:195], v[208:211], v[26:29]
	v_mfma_f32_16x16x32_bf16 v[18:21], v[184:187], v[216:219], v[18:21]
	v_mfma_f32_16x16x32_bf16 v[10:13], v[192:195], v[216:219], v[10:13]
	v_mfma_f32_16x16x32_bf16 v[6:9], v[184:187], v[224:227], v[6:9]
	v_mfma_f32_16x16x32_bf16 v[2:5], v[192:195], v[224:227], v[2:5]
	s_setprio 0
	s_barrier
	s_add_i32 s54, s54, 2
	s_addk_i32 s52, 0x100
	s_addk_i32 s53, 0x100
	s_cmp_gt_u32 s54, 13
	s_cbranch_scc0 .LBB0_121
	s_and_b64 vcc, exec, s[6:7]
	s_cbranch_vccz .LBB0_126
	s_barrier
	s_cmp_gt_i32 s46, 3
	s_mov_b64 s[16:17], -1
	s_cbranch_scc1 .LBB0_127

.LBB0_223:
	v_add_u32_e32 v150, 0x10000, v132
	v_add_u32_e32 v166, 0x14000, v132
	ds_read_b128 v[134:137], v150
	ds_read_b128 v[142:145], v150 offset:1024
	ds_read_b128 v[146:149], v150 offset:2048
	ds_read_b128 v[150:153], v150 offset:3072
	ds_read_b128 v[154:157], v166
	ds_read_b128 v[158:161], v166 offset:1024
	ds_read_b128 v[162:165], v166 offset:2048
	ds_read_b128 v[166:169], v166 offset:3072
	s_add_i32 s63, s39, s60
	s_add_i32 s62, s34, s60
	s_add_i32 s61, s63, 0x800
	s_addk_i32 s62, 0x800
	s_cmp_eq_u32 s60, 0
	s_cselect_b32 s64, s55, s61
	s_cselect_b32 s62, s58, s62
	s_or_b32 s61, s64, 0x80
	s_add_i32 s63, s63, 0x40780
	s_mov_b32 m0, s49
	s_nop 0
	buffer_load_dwordx4 v130, s[12:15], s63 offen lds
	s_nop 0
	s_mov_b32 m0, s50
	s_nop 0
	buffer_load_dwordx4 v131, s[12:15], s63 offen lds
	ds_read_b128 v[170:173], v133
	ds_read_b128 v[174:177], v133 offset:1024
	ds_read_b128 v[178:181], v133 offset:2048
	ds_read_b128 v[182:185], v133 offset:3072
	ds_read_b128 v[186:189], v133 offset:4096
	ds_read_b128 v[190:193], v133 offset:5120
	ds_read_b128 v[194:197], v133 offset:6144
	ds_read_b128 v[198:201], v133 offset:7168
	s_waitcnt vmcnt(8)
	s_waitcnt lgkmcnt(0)
	s_barrier
	s_setprio 1
	s_waitcnt lgkmcnt(7)
	v_mfma_f32_16x16x32_bf16 v[138:141], v[134:137], v[170:173], v[138:141]
	v_mfma_f32_16x16x32_bf16 v[126:129], v[146:149], v[170:173], v[126:129]
	s_waitcnt lgkmcnt(5)
	v_mfma_f32_16x16x32_bf16 v[110:113], v[134:137], v[178:181], v[110:113]
	v_mfma_f32_16x16x32_bf16 v[106:109], v[146:149], v[178:181], v[106:109]
	s_waitcnt lgkmcnt(3)
	v_mfma_f32_16x16x32_bf16 v[94:97], v[134:137], v[186:189], v[94:97]
	v_mfma_f32_16x16x32_bf16 v[90:93], v[146:149], v[186:189], v[90:93]
	s_waitcnt lgkmcnt(1)
	v_mfma_f32_16x16x32_bf16 v[78:81], v[134:137], v[194:197], v[78:81]
	v_mfma_f32_16x16x32_bf16 v[74:77], v[146:149], v[194:197], v[74:77]
	v_mfma_f32_16x16x32_bf16 v[138:141], v[142:145], v[174:177], v[138:141]
	v_mfma_f32_16x16x32_bf16 v[126:129], v[150:153], v[174:177], v[126:129]
	v_mfma_f32_16x16x32_bf16 v[110:113], v[142:145], v[182:185], v[110:113]
	v_mfma_f32_16x16x32_bf16 v[106:109], v[150:153], v[182:185], v[106:109]
	v_mfma_f32_16x16x32_bf16 v[94:97], v[142:145], v[190:193], v[94:97]
	v_mfma_f32_16x16x32_bf16 v[90:93], v[150:153], v[190:193], v[90:93]
	s_waitcnt lgkmcnt(0)
	v_mfma_f32_16x16x32_bf16 v[78:81], v[142:145], v[198:201], v[78:81]
	v_mfma_f32_16x16x32_bf16 v[74:77], v[150:153], v[198:201], v[74:77]
	s_setprio 0
	s_setprio 1
	v_mfma_f32_16x16x32_bf16 v[118:121], v[154:157], v[170:173], v[118:121]
	v_mfma_f32_16x16x32_bf16 v[114:117], v[162:165], v[170:173], v[114:117]
	v_mfma_f32_16x16x32_bf16 v[102:105], v[154:157], v[178:181], v[102:105]
	v_mfma_f32_16x16x32_bf16 v[98:101], v[162:165], v[178:181], v[98:101]
	v_mfma_f32_16x16x32_bf16 v[86:89], v[154:157], v[186:189], v[86:89]
	v_mfma_f32_16x16x32_bf16 v[82:85], v[162:165], v[186:189], v[82:85]
	v_mfma_f32_16x16x32_bf16 v[70:73], v[154:157], v[194:197], v[70:73]
	v_mfma_f32_16x16x32_bf16 v[66:69], v[162:165], v[194:197], v[66:69]
	v_mfma_f32_16x16x32_bf16 v[118:121], v[158:161], v[174:177], v[118:121]
	v_mfma_f32_16x16x32_bf16 v[114:117], v[166:169], v[174:177], v[114:117]
	v_mfma_f32_16x16x32_bf16 v[102:105], v[158:161], v[182:185], v[102:105]
	v_mfma_f32_16x16x32_bf16 v[98:101], v[166:169], v[182:185], v[98:101]
	v_mfma_f32_16x16x32_bf16 v[86:89], v[158:161], v[190:193], v[86:89]
	v_mfma_f32_16x16x32_bf16 v[82:85], v[166:169], v[190:193], v[82:85]
	v_mfma_f32_16x16x32_bf16 v[70:73], v[158:161], v[198:201], v[70:73]
	v_mfma_f32_16x16x32_bf16 v[66:69], v[166:169], v[198:201], v[66:69]
	s_setprio 0
	s_barrier
	ds_read_b128 v[170:173], v133 offset:16384
	ds_read_b128 v[174:177], v133 offset:17408
	s_mov_b32 m0, s33
	s_nop 0
	buffer_load_dwordx4 v130, s[8:11], s62 offen lds
	ds_read_b128 v[178:181], v133 offset:18432
	ds_read_b128 v[182:185], v133 offset:19456
	s_add_i32 s63, s62, 0x40000
	s_mov_b32 m0, s35
	s_nop 0
	buffer_load_dwordx4 v131, s[8:11], s62 offen lds
	ds_read_b128 v[186:189], v133 offset:20480
	ds_read_b128 v[190:193], v133 offset:21504
	s_nop 0
	s_mov_b32 m0, s36
	s_nop 0
	buffer_load_dwordx4 v130, s[8:11], s63 offen lds
	ds_read_b128 v[194:197], v133 offset:22528
	ds_read_b128 v[198:201], v133 offset:23552
	s_nop 0
	s_mov_b32 m0, s37
	s_nop 0
	buffer_load_dwordx4 v131, s[8:11], s63 offen lds
	s_nop 0
	s_mov_b32 m0, s31
	s_nop 0
	buffer_load_dwordx4 v130, s[12:15], s64 offen lds
	s_nop 0
	s_mov_b32 m0, s40
	s_nop 0
	buffer_load_dwordx4 v131, s[12:15], s64 offen lds
	s_waitcnt vmcnt(8)
	s_waitcnt lgkmcnt(0)
	s_barrier
	s_setprio 1
	s_waitcnt lgkmcnt(7)
	v_mfma_f32_16x16x32_bf16 v[62:65], v[134:137], v[170:173], v[62:65]
	v_mfma_f32_16x16x32_bf16 v[58:61], v[146:149], v[170:173], v[58:61]
	s_waitcnt lgkmcnt(5)
	v_mfma_f32_16x16x32_bf16 v[46:49], v[134:137], v[178:181], v[46:49]
	v_mfma_f32_16x16x32_bf16 v[42:45], v[146:149], v[178:181], v[42:45]
	s_waitcnt lgkmcnt(3)
	v_mfma_f32_16x16x32_bf16 v[30:33], v[134:137], v[186:189], v[30:33]
	v_mfma_f32_16x16x32_bf16 v[26:29], v[146:149], v[186:189], v[26:29]
	s_waitcnt lgkmcnt(1)
	v_mfma_f32_16x16x32_bf16 v[14:17], v[134:137], v[194:197], v[14:17]
	v_mfma_f32_16x16x32_bf16 v[10:13], v[146:149], v[194:197], v[10:13]
	v_mfma_f32_16x16x32_bf16 v[62:65], v[142:145], v[174:177], v[62:65]
	v_mfma_f32_16x16x32_bf16 v[58:61], v[150:153], v[174:177], v[58:61]
	v_mfma_f32_16x16x32_bf16 v[46:49], v[142:145], v[182:185], v[46:49]
	v_mfma_f32_16x16x32_bf16 v[42:45], v[150:153], v[182:185], v[42:45]
	v_mfma_f32_16x16x32_bf16 v[30:33], v[142:145], v[190:193], v[30:33]
	v_mfma_f32_16x16x32_bf16 v[26:29], v[150:153], v[190:193], v[26:29]
	s_waitcnt lgkmcnt(0)
	v_mfma_f32_16x16x32_bf16 v[14:17], v[142:145], v[198:201], v[14:17]
	v_mfma_f32_16x16x32_bf16 v[10:13], v[150:153], v[198:201], v[10:13]
	s_setprio 0
	s_setprio 1
	v_mfma_f32_16x16x32_bf16 v[54:57], v[154:157], v[170:173], v[54:57]
	v_mfma_f32_16x16x32_bf16 v[50:53], v[162:165], v[170:173], v[50:53]
	v_mfma_f32_16x16x32_bf16 v[38:41], v[154:157], v[178:181], v[38:41]
	v_mfma_f32_16x16x32_bf16 v[34:37], v[162:165], v[178:181], v[34:37]
	v_mfma_f32_16x16x32_bf16 v[22:25], v[154:157], v[186:189], v[22:25]
	v_mfma_f32_16x16x32_bf16 v[18:21], v[162:165], v[186:189], v[18:21]
	v_mfma_f32_16x16x32_bf16 v[6:9], v[154:157], v[194:197], v[6:9]
	v_mfma_f32_16x16x32_bf16 v[2:5], v[162:165], v[194:197], v[2:5]
	v_mfma_f32_16x16x32_bf16 v[54:57], v[158:161], v[174:177], v[54:57]
	v_mfma_f32_16x16x32_bf16 v[50:53], v[166:169], v[174:177], v[50:53]
	v_mfma_f32_16x16x32_bf16 v[38:41], v[158:161], v[182:185], v[38:41]
	v_mfma_f32_16x16x32_bf16 v[34:37], v[166:169], v[182:185], v[34:37]
	v_mfma_f32_16x16x32_bf16 v[22:25], v[158:161], v[190:193], v[22:25]
	v_mfma_f32_16x16x32_bf16 v[18:21], v[166:169], v[190:193], v[18:21]
	v_mfma_f32_16x16x32_bf16 v[6:9], v[158:161], v[198:201], v[6:9]
	v_mfma_f32_16x16x32_bf16 v[2:5], v[166:169], v[198:201], v[2:5]
	s_setprio 0
	s_barrier
	v_add_u32_e32 v150, 0x18000, v132
	v_add_u32_e32 v166, 0x1c000, v132
	ds_read_b128 v[134:137], v150
	ds_read_b128 v[142:145], v150 offset:1024
	ds_read_b128 v[146:149], v150 offset:2048
	ds_read_b128 v[150:153], v150 offset:3072
	ds_read_b128 v[154:157], v166
	ds_read_b128 v[158:161], v166 offset:1024
	ds_read_b128 v[162:165], v166 offset:2048
	ds_read_b128 v[166:169], v166 offset:3072
	s_add_i32 s63, s64, 0x40000
	s_mov_b32 m0, s41
	s_nop 0
	buffer_load_dwordx4 v130, s[12:15], s63 offen lds
	s_nop 0
	s_mov_b32 m0, s42
	s_nop 0
	buffer_load_dwordx4 v131, s[12:15], s63 offen lds
	ds_read_b128 v[170:173], v133 offset:32768
	ds_read_b128 v[174:177], v133 offset:33792
	ds_read_b128 v[178:181], v133 offset:34816
	ds_read_b128 v[182:185], v133 offset:35840
	ds_read_b128 v[186:189], v133 offset:36864
	ds_read_b128 v[190:193], v133 offset:37888
	ds_read_b128 v[194:197], v133 offset:38912
	ds_read_b128 v[198:201], v133 offset:39936
	s_waitcnt vmcnt(8)
	s_waitcnt lgkmcnt(0)
	s_barrier
	s_setprio 1
	s_waitcnt lgkmcnt(7)
	v_mfma_f32_16x16x32_bf16 v[138:141], v[134:137], v[170:173], v[138:141]
	v_mfma_f32_16x16x32_bf16 v[126:129], v[146:149], v[170:173], v[126:129]
	s_waitcnt lgkmcnt(5)
	v_mfma_f32_16x16x32_bf16 v[110:113], v[134:137], v[178:181], v[110:113]
	v_mfma_f32_16x16x32_bf16 v[106:109], v[146:149], v[178:181], v[106:109]
	s_waitcnt lgkmcnt(3)
	v_mfma_f32_16x16x32_bf16 v[94:97], v[134:137], v[186:189], v[94:97]
	v_mfma_f32_16x16x32_bf16 v[90:93], v[146:149], v[186:189], v[90:93]
	s_waitcnt lgkmcnt(1)
	v_mfma_f32_16x16x32_bf16 v[78:81], v[134:137], v[194:197], v[78:81]
	v_mfma_f32_16x16x32_bf16 v[74:77], v[146:149], v[194:197], v[74:77]
	v_mfma_f32_16x16x32_bf16 v[138:141], v[142:145], v[174:177], v[138:141]
	v_mfma_f32_16x16x32_bf16 v[126:129], v[150:153], v[174:177], v[126:129]
	v_mfma_f32_16x16x32_bf16 v[110:113], v[142:145], v[182:185], v[110:113]
	v_mfma_f32_16x16x32_bf16 v[106:109], v[150:153], v[182:185], v[106:109]
	v_mfma_f32_16x16x32_bf16 v[94:97], v[142:145], v[190:193], v[94:97]
	v_mfma_f32_16x16x32_bf16 v[90:93], v[150:153], v[190:193], v[90:93]
	s_waitcnt lgkmcnt(0)
	v_mfma_f32_16x16x32_bf16 v[78:81], v[142:145], v[198:201], v[78:81]
	v_mfma_f32_16x16x32_bf16 v[74:77], v[150:153], v[198:201], v[74:77]
	s_setprio 0
	s_setprio 1
	v_mfma_f32_16x16x32_bf16 v[118:121], v[154:157], v[170:173], v[118:121]
	v_mfma_f32_16x16x32_bf16 v[114:117], v[162:165], v[170:173], v[114:117]
	v_mfma_f32_16x16x32_bf16 v[102:105], v[154:157], v[178:181], v[102:105]
	v_mfma_f32_16x16x32_bf16 v[98:101], v[162:165], v[178:181], v[98:101]
	v_mfma_f32_16x16x32_bf16 v[86:89], v[154:157], v[186:189], v[86:89]
	v_mfma_f32_16x16x32_bf16 v[82:85], v[162:165], v[186:189], v[82:85]
	v_mfma_f32_16x16x32_bf16 v[70:73], v[154:157], v[194:197], v[70:73]
	v_mfma_f32_16x16x32_bf16 v[66:69], v[162:165], v[194:197], v[66:69]
	v_mfma_f32_16x16x32_bf16 v[118:121], v[158:161], v[174:177], v[118:121]
	v_mfma_f32_16x16x32_bf16 v[114:117], v[166:169], v[174:177], v[114:117]
	v_mfma_f32_16x16x32_bf16 v[102:105], v[158:161], v[182:185], v[102:105]
	v_mfma_f32_16x16x32_bf16 v[98:101], v[166:169], v[182:185], v[98:101]
	v_mfma_f32_16x16x32_bf16 v[86:89], v[158:161], v[190:193], v[86:89]
	v_mfma_f32_16x16x32_bf16 v[82:85], v[166:169], v[190:193], v[82:85]
	v_mfma_f32_16x16x32_bf16 v[70:73], v[158:161], v[198:201], v[70:73]
	v_mfma_f32_16x16x32_bf16 v[66:69], v[166:169], v[198:201], v[66:69]
	s_setprio 0
	s_barrier
	ds_read_b128 v[170:173], v133 offset:49152
	ds_read_b128 v[174:177], v133 offset:50176
	s_or_b32 s63, s62, 0x80
	s_mov_b32 m0, s43
	s_nop 0
	buffer_load_dwordx4 v130, s[8:11], s63 offen lds
	ds_read_b128 v[178:181], v133 offset:51200
	ds_read_b128 v[182:185], v133 offset:52224
	s_add_i32 s62, s62, 0x40080
	s_mov_b32 m0, s44
	s_nop 0
	buffer_load_dwordx4 v131, s[8:11], s63 offen lds
	ds_read_b128 v[186:189], v133 offset:53248
	ds_read_b128 v[190:193], v133 offset:54272
	s_nop 0
	s_mov_b32 m0, s47
	s_nop 0
	buffer_load_dwordx4 v130, s[8:11], s62 offen lds
	ds_read_b128 v[194:197], v133 offset:55296
	ds_read_b128 v[198:201], v133 offset:56320
	s_nop 0
	s_mov_b32 m0, s48
	s_nop 0
	buffer_load_dwordx4 v131, s[8:11], s62 offen lds
	s_nop 0
	s_mov_b32 m0, s45
	s_nop 0
	buffer_load_dwordx4 v130, s[12:15], s61 offen lds
	s_nop 0
	s_mov_b32 m0, s46
	s_nop 0
	buffer_load_dwordx4 v131, s[12:15], s61 offen lds
	s_waitcnt vmcnt(8)
	s_waitcnt lgkmcnt(0)
	s_barrier
	s_setprio 1
	s_waitcnt lgkmcnt(7)
	v_mfma_f32_16x16x32_bf16 v[62:65], v[134:137], v[170:173], v[62:65]
	v_mfma_f32_16x16x32_bf16 v[58:61], v[146:149], v[170:173], v[58:61]
	s_waitcnt lgkmcnt(5)
	v_mfma_f32_16x16x32_bf16 v[46:49], v[134:137], v[178:181], v[46:49]
	v_mfma_f32_16x16x32_bf16 v[42:45], v[146:149], v[178:181], v[42:45]
	s_waitcnt lgkmcnt(3)
	v_mfma_f32_16x16x32_bf16 v[30:33], v[134:137], v[186:189], v[30:33]
	v_mfma_f32_16x16x32_bf16 v[26:29], v[146:149], v[186:189], v[26:29]
	s_waitcnt lgkmcnt(1)
	v_mfma_f32_16x16x32_bf16 v[14:17], v[134:137], v[194:197], v[14:17]
	v_mfma_f32_16x16x32_bf16 v[10:13], v[146:149], v[194:197], v[10:13]
	v_mfma_f32_16x16x32_bf16 v[62:65], v[142:145], v[174:177], v[62:65]
	v_mfma_f32_16x16x32_bf16 v[58:61], v[150:153], v[174:177], v[58:61]
	v_mfma_f32_16x16x32_bf16 v[46:49], v[142:145], v[182:185], v[46:49]
	v_mfma_f32_16x16x32_bf16 v[42:45], v[150:153], v[182:185], v[42:45]
	v_mfma_f32_16x16x32_bf16 v[30:33], v[142:145], v[190:193], v[30:33]
	v_mfma_f32_16x16x32_bf16 v[26:29], v[150:153], v[190:193], v[26:29]
	s_waitcnt lgkmcnt(0)
	v_mfma_f32_16x16x32_bf16 v[14:17], v[142:145], v[198:201], v[14:17]
	v_mfma_f32_16x16x32_bf16 v[10:13], v[150:153], v[198:201], v[10:13]
	s_setprio 0
	s_setprio 1
	v_mfma_f32_16x16x32_bf16 v[54:57], v[154:157], v[170:173], v[54:57]
	v_mfma_f32_16x16x32_bf16 v[50:53], v[162:165], v[170:173], v[50:53]
	v_mfma_f32_16x16x32_bf16 v[38:41], v[154:157], v[178:181], v[38:41]
	v_mfma_f32_16x16x32_bf16 v[34:37], v[162:165], v[178:181], v[34:37]
	v_mfma_f32_16x16x32_bf16 v[22:25], v[154:157], v[186:189], v[22:25]
	v_mfma_f32_16x16x32_bf16 v[18:21], v[162:165], v[186:189], v[18:21]
	v_mfma_f32_16x16x32_bf16 v[6:9], v[154:157], v[194:197], v[6:9]
	v_mfma_f32_16x16x32_bf16 v[2:5], v[162:165], v[194:197], v[2:5]
	v_mfma_f32_16x16x32_bf16 v[54:57], v[158:161], v[174:177], v[54:57]
	v_mfma_f32_16x16x32_bf16 v[50:53], v[166:169], v[174:177], v[50:53]
	v_mfma_f32_16x16x32_bf16 v[38:41], v[158:161], v[182:185], v[38:41]
	v_mfma_f32_16x16x32_bf16 v[34:37], v[166:169], v[182:185], v[34:37]
	v_mfma_f32_16x16x32_bf16 v[22:25], v[158:161], v[190:193], v[22:25]
	v_mfma_f32_16x16x32_bf16 v[18:21], v[166:169], v[190:193], v[18:21]
	v_mfma_f32_16x16x32_bf16 v[6:9], v[158:161], v[198:201], v[6:9]
	v_mfma_f32_16x16x32_bf16 v[2:5], v[166:169], v[198:201], v[2:5]
	s_setprio 0
	s_barrier
	s_add_i32 s59, s59, 2
	s_addk_i32 s60, 0x100
	s_cmp_gt_u32 s59, 13
	s_cbranch_scc0 .LBB0_223
	s_andn2_b64 vcc, exec, s[6:7]
	s_cbranch_vccnz .LBB0_215
	v_mov_b32_e32 v2, 0
	s_mov_b32 s18, s52
	s_mov_b32 s29, s53
	s_mov_b32 s34, s3
	s_mov_b32 s39, s2
	s_mov_b32 s51, s54
	v_mov_b32_e32 v3, v2
	v_mov_b32_e32 v4, v2
	v_mov_b32_e32 v5, v2
	v_mov_b32_e32 v6, v2
	v_mov_b32_e32 v7, v2
	v_mov_b32_e32 v8, v2
	v_mov_b32_e32 v9, v2
	v_mov_b32_e32 v18, v2
	v_mov_b32_e32 v19, v2
	v_mov_b32_e32 v20, v2
	v_mov_b32_e32 v21, v2
	v_mov_b32_e32 v22, v2
	v_mov_b32_e32 v23, v2
	v_mov_b32_e32 v24, v2
	v_mov_b32_e32 v25, v2
	v_mov_b32_e32 v34, v2
	v_mov_b32_e32 v35, v2
	v_mov_b32_e32 v36, v2
	v_mov_b32_e32 v37, v2
	v_mov_b32_e32 v38, v2
	v_mov_b32_e32 v39, v2
	v_mov_b32_e32 v40, v2
	v_mov_b32_e32 v41, v2
	v_mov_b32_e32 v50, v2
	v_mov_b32_e32 v51, v2
	v_mov_b32_e32 v52, v2
	v_mov_b32_e32 v53, v2
	v_mov_b32_e32 v54, v2
	v_mov_b32_e32 v55, v2
	v_mov_b32_e32 v56, v2
	v_mov_b32_e32 v57, v2
	v_mov_b32_e32 v10, v2
	v_mov_b32_e32 v11, v2
	v_mov_b32_e32 v12, v2
	v_mov_b32_e32 v13, v2
	v_mov_b32_e32 v14, v2
	v_mov_b32_e32 v15, v2
	v_mov_b32_e32 v16, v2
	v_mov_b32_e32 v17, v2
	v_mov_b32_e32 v26, v2
	v_mov_b32_e32 v27, v2
	v_mov_b32_e32 v28, v2
	v_mov_b32_e32 v29, v2
	v_mov_b32_e32 v30, v2
	v_mov_b32_e32 v31, v2
	v_mov_b32_e32 v32, v2
	v_mov_b32_e32 v33, v2
	v_mov_b32_e32 v42, v2
	v_mov_b32_e32 v43, v2
	v_mov_b32_e32 v44, v2
	v_mov_b32_e32 v45, v2
	v_mov_b32_e32 v46, v2
	v_mov_b32_e32 v47, v2
	v_mov_b32_e32 v48, v2
	v_mov_b32_e32 v49, v2
	v_mov_b32_e32 v58, v2
	v_mov_b32_e32 v59, v2
	v_mov_b32_e32 v60, v2
	v_mov_b32_e32 v61, v2
	v_mov_b32_e32 v62, v2
	v_mov_b32_e32 v63, v2
	v_mov_b32_e32 v64, v2
	v_mov_b32_e32 v65, v2
	v_mov_b32_e32 v66, v2
	v_mov_b32_e32 v67, v2
	v_mov_b32_e32 v68, v2
	v_mov_b32_e32 v69, v2
	v_mov_b32_e32 v70, v2
	v_mov_b32_e32 v71, v2
	v_mov_b32_e32 v72, v2
	v_mov_b32_e32 v73, v2
	v_mov_b32_e32 v82, v2
	v_mov_b32_e32 v83, v2
	v_mov_b32_e32 v84, v2
	v_mov_b32_e32 v85, v2
	v_mov_b32_e32 v86, v2
	v_mov_b32_e32 v87, v2
	v_mov_b32_e32 v88, v2
	v_mov_b32_e32 v89, v2
	v_mov_b32_e32 v98, v2
	v_mov_b32_e32 v99, v2
	v_mov_b32_e32 v100, v2
	v_mov_b32_e32 v101, v2
	v_mov_b32_e32 v102, v2
	v_mov_b32_e32 v103, v2
	v_mov_b32_e32 v104, v2
	v_mov_b32_e32 v105, v2
	v_mov_b32_e32 v114, v2
	v_mov_b32_e32 v115, v2
	v_mov_b32_e32 v116, v2
	v_mov_b32_e32 v117, v2
	v_mov_b32_e32 v118, v2
	v_mov_b32_e32 v119, v2
	v_mov_b32_e32 v120, v2
	v_mov_b32_e32 v121, v2
	v_mov_b32_e32 v74, v2
	v_mov_b32_e32 v75, v2
	v_mov_b32_e32 v76, v2
	v_mov_b32_e32 v77, v2
	v_mov_b32_e32 v78, v2
	v_mov_b32_e32 v79, v2
	v_mov_b32_e32 v80, v2
	v_mov_b32_e32 v81, v2
	v_mov_b32_e32 v90, v2
	v_mov_b32_e32 v91, v2
	v_mov_b32_e32 v92, v2
	v_mov_b32_e32 v93, v2
	v_mov_b32_e32 v94, v2
	v_mov_b32_e32 v95, v2
	v_mov_b32_e32 v96, v2
	v_mov_b32_e32 v97, v2
	v_mov_b32_e32 v106, v2
	v_mov_b32_e32 v107, v2
	v_mov_b32_e32 v108, v2
	v_mov_b32_e32 v109, v2
	v_mov_b32_e32 v110, v2
	v_mov_b32_e32 v111, v2
	v_mov_b32_e32 v112, v2
	v_mov_b32_e32 v113, v2
	v_mov_b32_e32 v126, v2
	v_mov_b32_e32 v127, v2
	v_mov_b32_e32 v128, v2
	v_mov_b32_e32 v129, v2
	v_mov_b32_e32 v138, v2
	v_mov_b32_e32 v139, v2
	v_mov_b32_e32 v140, v2
	v_mov_b32_e32 v141, v2
	s_branch .LBB0_215

.LBB0_353:
	ds_read_b128 v[136:139], v153
	ds_read_b128 v[140:143], v153 offset:1024
	ds_read_b128 v[158:161], v153 offset:2048
	ds_read_b128 v[162:165], v153 offset:3072
	ds_read_b128 v[166:169], v154
	ds_read_b128 v[170:173], v154 offset:1024
	ds_read_b128 v[174:177], v154 offset:2048
	ds_read_b128 v[178:181], v154 offset:3072
	s_add_i32 s66, s63, 0xfffe0080
	s_cmp_eq_u32 s65, 4
	s_cselect_b32 s68, s1, s66
	s_cselect_b32 s67, s62, s64
	s_or_b32 s66, s68, 0x80
	s_mov_b32 m0, s48
	s_nop 0
	buffer_load_dwordx4 v147, s[12:15], s63 offen lds
	s_nop 0
	s_mov_b32 m0, s49
	s_nop 0
	buffer_load_dwordx4 v148, s[12:15], s63 offen lds
	ds_read_b128 v[182:185], v155
	ds_read_b128 v[186:189], v155 offset:1024
	ds_read_b128 v[190:193], v155 offset:2048
	ds_read_b128 v[194:197], v155 offset:3072
	ds_read_b128 v[198:201], v155 offset:4096
	ds_read_b128 v[202:205], v155 offset:5120
	ds_read_b128 v[206:209], v155 offset:6144
	ds_read_b128 v[210:213], v155 offset:7168
	s_waitcnt vmcnt(8)
	s_waitcnt lgkmcnt(0)
	s_barrier
	s_setprio 1
	s_waitcnt lgkmcnt(0)
	v_mfma_i32_16x16x64_i8 v[126:129], v[136:139], v[182:185], v[126:129]
	v_mfma_i32_16x16x64_i8 v[122:125], v[158:161], v[182:185], v[122:125]
	v_mfma_i32_16x16x64_i8 v[118:121], v[136:139], v[190:193], v[118:121]
	v_mfma_i32_16x16x64_i8 v[114:117], v[158:161], v[190:193], v[114:117]
	v_mfma_i32_16x16x64_i8 v[110:113], v[136:139], v[198:201], v[110:113]
	v_mfma_i32_16x16x64_i8 v[106:109], v[158:161], v[198:201], v[106:109]
	v_mfma_i32_16x16x64_i8 v[102:105], v[136:139], v[206:209], v[102:105]
	v_mfma_i32_16x16x64_i8 v[98:101], v[158:161], v[206:209], v[98:101]
	v_mfma_i32_16x16x64_i8 v[126:129], v[140:143], v[186:189], v[126:129]
	v_mfma_i32_16x16x64_i8 v[122:125], v[162:165], v[186:189], v[122:125]
	v_mfma_i32_16x16x64_i8 v[118:121], v[140:143], v[194:197], v[118:121]
	v_mfma_i32_16x16x64_i8 v[114:117], v[162:165], v[194:197], v[114:117]
	v_mfma_i32_16x16x64_i8 v[110:113], v[140:143], v[202:205], v[110:113]
	v_mfma_i32_16x16x64_i8 v[106:109], v[162:165], v[202:205], v[106:109]
	v_mfma_i32_16x16x64_i8 v[102:105], v[140:143], v[210:213], v[102:105]
	v_mfma_i32_16x16x64_i8 v[98:101], v[162:165], v[210:213], v[98:101]
	s_setprio 0
	s_setprio 1
	v_mfma_i32_16x16x64_i8 v[94:97], v[166:169], v[182:185], v[94:97]
	v_mfma_i32_16x16x64_i8 v[90:93], v[174:177], v[182:185], v[90:93]
	v_mfma_i32_16x16x64_i8 v[86:89], v[166:169], v[190:193], v[86:89]
	v_mfma_i32_16x16x64_i8 v[82:85], v[174:177], v[190:193], v[82:85]
	v_mfma_i32_16x16x64_i8 v[78:81], v[166:169], v[198:201], v[78:81]
	v_mfma_i32_16x16x64_i8 v[74:77], v[174:177], v[198:201], v[74:77]
	v_mfma_i32_16x16x64_i8 v[70:73], v[166:169], v[206:209], v[70:73]
	v_mfma_i32_16x16x64_i8 v[66:69], v[174:177], v[206:209], v[66:69]
	v_mfma_i32_16x16x64_i8 v[94:97], v[170:173], v[186:189], v[94:97]
	v_mfma_i32_16x16x64_i8 v[90:93], v[178:181], v[186:189], v[90:93]
	v_mfma_i32_16x16x64_i8 v[86:89], v[170:173], v[194:197], v[86:89]
	v_mfma_i32_16x16x64_i8 v[82:85], v[178:181], v[194:197], v[82:85]
	v_mfma_i32_16x16x64_i8 v[78:81], v[170:173], v[202:205], v[78:81]
	v_mfma_i32_16x16x64_i8 v[74:77], v[178:181], v[202:205], v[74:77]
	v_mfma_i32_16x16x64_i8 v[70:73], v[170:173], v[210:213], v[70:73]
	v_mfma_i32_16x16x64_i8 v[66:69], v[178:181], v[210:213], v[66:69]
	s_setprio 0
	s_barrier
	ds_read_b128 v[182:185], v155 offset:16384
	ds_read_b128 v[186:189], v155 offset:17408
	s_mov_b32 m0, s34
	s_nop 0
	buffer_load_dwordx4 v145, s[8:11], s67 offen lds
	ds_read_b128 v[190:193], v155 offset:18432
	ds_read_b128 v[194:197], v155 offset:19456
	s_add_i32 s69, s67, 0x20000
	s_mov_b32 m0, s35
	s_nop 0
	buffer_load_dwordx4 v146, s[8:11], s67 offen lds
	ds_read_b128 v[198:201], v155 offset:20480
	ds_read_b128 v[202:205], v155 offset:21504
	s_nop 0
	s_mov_b32 m0, s36
	s_nop 0
	buffer_load_dwordx4 v145, s[8:11], s69 offen lds
	ds_read_b128 v[206:209], v155 offset:22528
	ds_read_b128 v[210:213], v155 offset:23552
	s_nop 0
	s_mov_b32 m0, s37
	s_nop 0
	buffer_load_dwordx4 v146, s[8:11], s69 offen lds
	s_nop 0
	s_mov_b32 m0, s33
	s_nop 0
	buffer_load_dwordx4 v147, s[12:15], s68 offen lds
	s_nop 0
	s_mov_b32 m0, s2
	s_nop 0
	buffer_load_dwordx4 v148, s[12:15], s68 offen lds
	s_waitcnt vmcnt(8)
	s_waitcnt lgkmcnt(0)
	s_barrier
	s_setprio 1
	s_waitcnt lgkmcnt(0)
	v_mfma_i32_16x16x64_i8 v[62:65], v[136:139], v[182:185], v[62:65]
	v_mfma_i32_16x16x64_i8 v[58:61], v[158:161], v[182:185], v[58:61]
	v_mfma_i32_16x16x64_i8 v[54:57], v[136:139], v[190:193], v[54:57]
	v_mfma_i32_16x16x64_i8 v[50:53], v[158:161], v[190:193], v[50:53]
	v_mfma_i32_16x16x64_i8 v[46:49], v[136:139], v[198:201], v[46:49]
	v_mfma_i32_16x16x64_i8 v[42:45], v[158:161], v[198:201], v[42:45]
	v_mfma_i32_16x16x64_i8 v[38:41], v[136:139], v[206:209], v[38:41]
	v_mfma_i32_16x16x64_i8 v[34:37], v[158:161], v[206:209], v[34:37]
	v_mfma_i32_16x16x64_i8 v[62:65], v[140:143], v[186:189], v[62:65]
	v_mfma_i32_16x16x64_i8 v[58:61], v[162:165], v[186:189], v[58:61]
	v_mfma_i32_16x16x64_i8 v[54:57], v[140:143], v[194:197], v[54:57]
	v_mfma_i32_16x16x64_i8 v[50:53], v[162:165], v[194:197], v[50:53]
	v_mfma_i32_16x16x64_i8 v[46:49], v[140:143], v[202:205], v[46:49]
	v_mfma_i32_16x16x64_i8 v[42:45], v[162:165], v[202:205], v[42:45]
	v_mfma_i32_16x16x64_i8 v[38:41], v[140:143], v[210:213], v[38:41]
	v_mfma_i32_16x16x64_i8 v[34:37], v[162:165], v[210:213], v[34:37]
	s_setprio 0
	s_setprio 1
	v_mfma_i32_16x16x64_i8 v[30:33], v[166:169], v[182:185], v[30:33]
	v_mfma_i32_16x16x64_i8 v[26:29], v[174:177], v[182:185], v[26:29]
	v_mfma_i32_16x16x64_i8 v[22:25], v[166:169], v[190:193], v[22:25]
	v_mfma_i32_16x16x64_i8 v[18:21], v[174:177], v[190:193], v[18:21]
	v_mfma_i32_16x16x64_i8 v[14:17], v[166:169], v[198:201], v[14:17]
	v_mfma_i32_16x16x64_i8 v[10:13], v[174:177], v[198:201], v[10:13]
	v_mfma_i32_16x16x64_i8 v[6:9], v[166:169], v[206:209], v[6:9]
	v_mfma_i32_16x16x64_i8 v[2:5], v[174:177], v[206:209], v[2:5]
	v_mfma_i32_16x16x64_i8 v[30:33], v[170:173], v[186:189], v[30:33]
	v_mfma_i32_16x16x64_i8 v[26:29], v[178:181], v[186:189], v[26:29]
	v_mfma_i32_16x16x64_i8 v[22:25], v[170:173], v[194:197], v[22:25]
	v_mfma_i32_16x16x64_i8 v[18:21], v[178:181], v[194:197], v[18:21]
	v_mfma_i32_16x16x64_i8 v[14:17], v[170:173], v[202:205], v[14:17]
	v_mfma_i32_16x16x64_i8 v[10:13], v[178:181], v[202:205], v[10:13]
	v_mfma_i32_16x16x64_i8 v[6:9], v[170:173], v[210:213], v[6:9]
	v_mfma_i32_16x16x64_i8 v[2:5], v[178:181], v[210:213], v[2:5]
	s_setprio 0
	s_barrier
	ds_read_b128 v[136:139], v156
	ds_read_b128 v[140:143], v156 offset:1024
	ds_read_b128 v[158:161], v156 offset:2048
	ds_read_b128 v[162:165], v156 offset:3072
	ds_read_b128 v[166:169], v157
	ds_read_b128 v[170:173], v157 offset:1024
	ds_read_b128 v[174:177], v157 offset:2048
	ds_read_b128 v[178:181], v157 offset:3072
	s_add_i32 s68, s68, 0x20000
	s_mov_b32 m0, s3
	s_nop 0
	buffer_load_dwordx4 v147, s[12:15], s68 offen lds
	s_nop 0
	s_mov_b32 m0, s38
	s_nop 0
	buffer_load_dwordx4 v148, s[12:15], s68 offen lds
	ds_read_b128 v[182:185], v155 offset:32768
	ds_read_b128 v[186:189], v155 offset:33792
	ds_read_b128 v[190:193], v155 offset:34816
	ds_read_b128 v[194:197], v155 offset:35840
	ds_read_b128 v[198:201], v155 offset:36864
	ds_read_b128 v[202:205], v155 offset:37888
	ds_read_b128 v[206:209], v155 offset:38912
	ds_read_b128 v[210:213], v155 offset:39936
	s_waitcnt vmcnt(8)
	s_waitcnt lgkmcnt(0)
	s_barrier
	s_setprio 1
	s_waitcnt lgkmcnt(0)
	v_mfma_i32_16x16x64_i8 v[126:129], v[136:139], v[182:185], v[126:129]
	v_mfma_i32_16x16x64_i8 v[122:125], v[158:161], v[182:185], v[122:125]
	v_mfma_i32_16x16x64_i8 v[118:121], v[136:139], v[190:193], v[118:121]
	v_mfma_i32_16x16x64_i8 v[114:117], v[158:161], v[190:193], v[114:117]
	v_mfma_i32_16x16x64_i8 v[110:113], v[136:139], v[198:201], v[110:113]
	v_mfma_i32_16x16x64_i8 v[106:109], v[158:161], v[198:201], v[106:109]
	v_mfma_i32_16x16x64_i8 v[102:105], v[136:139], v[206:209], v[102:105]
	v_mfma_i32_16x16x64_i8 v[98:101], v[158:161], v[206:209], v[98:101]
	v_mfma_i32_16x16x64_i8 v[126:129], v[140:143], v[186:189], v[126:129]
	v_mfma_i32_16x16x64_i8 v[122:125], v[162:165], v[186:189], v[122:125]
	v_mfma_i32_16x16x64_i8 v[118:121], v[140:143], v[194:197], v[118:121]
	v_mfma_i32_16x16x64_i8 v[114:117], v[162:165], v[194:197], v[114:117]
	v_mfma_i32_16x16x64_i8 v[110:113], v[140:143], v[202:205], v[110:113]
	v_mfma_i32_16x16x64_i8 v[106:109], v[162:165], v[202:205], v[106:109]
	v_mfma_i32_16x16x64_i8 v[102:105], v[140:143], v[210:213], v[102:105]
	v_mfma_i32_16x16x64_i8 v[98:101], v[162:165], v[210:213], v[98:101]
	s_setprio 0
	s_setprio 1
	v_mfma_i32_16x16x64_i8 v[94:97], v[166:169], v[182:185], v[94:97]
	v_mfma_i32_16x16x64_i8 v[90:93], v[174:177], v[182:185], v[90:93]
	v_mfma_i32_16x16x64_i8 v[86:89], v[166:169], v[190:193], v[86:89]
	v_mfma_i32_16x16x64_i8 v[82:85], v[174:177], v[190:193], v[82:85]
	v_mfma_i32_16x16x64_i8 v[78:81], v[166:169], v[198:201], v[78:81]
	v_mfma_i32_16x16x64_i8 v[74:77], v[174:177], v[198:201], v[74:77]
	v_mfma_i32_16x16x64_i8 v[70:73], v[166:169], v[206:209], v[70:73]
	v_mfma_i32_16x16x64_i8 v[66:69], v[174:177], v[206:209], v[66:69]
	v_mfma_i32_16x16x64_i8 v[94:97], v[170:173], v[186:189], v[94:97]
	v_mfma_i32_16x16x64_i8 v[90:93], v[178:181], v[186:189], v[90:93]
	v_mfma_i32_16x16x64_i8 v[86:89], v[170:173], v[194:197], v[86:89]
	v_mfma_i32_16x16x64_i8 v[82:85], v[178:181], v[194:197], v[82:85]
	v_mfma_i32_16x16x64_i8 v[78:81], v[170:173], v[202:205], v[78:81]
	v_mfma_i32_16x16x64_i8 v[74:77], v[178:181], v[202:205], v[74:77]
	v_mfma_i32_16x16x64_i8 v[70:73], v[170:173], v[210:213], v[70:73]
	v_mfma_i32_16x16x64_i8 v[66:69], v[178:181], v[210:213], v[66:69]
	s_setprio 0
	s_barrier
	ds_read_b128 v[182:185], v155 offset:49152
	ds_read_b128 v[186:189], v155 offset:50176
	s_or_b32 s68, s67, 0x80
	s_mov_b32 m0, s41
	s_nop 0
	buffer_load_dwordx4 v145, s[8:11], s68 offen lds
	ds_read_b128 v[190:193], v155 offset:51200
	ds_read_b128 v[194:197], v155 offset:52224
	s_add_i32 s67, s67, 0x20080
	s_mov_b32 m0, s42
	s_nop 0
	buffer_load_dwordx4 v146, s[8:11], s68 offen lds
	ds_read_b128 v[198:201], v155 offset:53248
	ds_read_b128 v[202:205], v155 offset:54272
	s_nop 0
	s_mov_b32 m0, s45
	s_nop 0
	buffer_load_dwordx4 v145, s[8:11], s67 offen lds
	ds_read_b128 v[206:209], v155 offset:55296
	ds_read_b128 v[210:213], v155 offset:56320
	s_nop 0
	s_mov_b32 m0, s46
	s_nop 0
	buffer_load_dwordx4 v146, s[8:11], s67 offen lds
	s_nop 0
	s_mov_b32 m0, s43
	s_nop 0
	buffer_load_dwordx4 v147, s[12:15], s66 offen lds
	s_nop 0
	s_mov_b32 m0, s44
	s_nop 0
	buffer_load_dwordx4 v148, s[12:15], s66 offen lds
	s_waitcnt vmcnt(8)
	s_waitcnt lgkmcnt(0)
	s_barrier
	s_setprio 1
	s_waitcnt lgkmcnt(0)
	v_mfma_i32_16x16x64_i8 v[62:65], v[136:139], v[182:185], v[62:65]
	v_mfma_i32_16x16x64_i8 v[58:61], v[158:161], v[182:185], v[58:61]
	v_mfma_i32_16x16x64_i8 v[54:57], v[136:139], v[190:193], v[54:57]
	v_mfma_i32_16x16x64_i8 v[50:53], v[158:161], v[190:193], v[50:53]
	v_mfma_i32_16x16x64_i8 v[46:49], v[136:139], v[198:201], v[46:49]
	v_mfma_i32_16x16x64_i8 v[42:45], v[158:161], v[198:201], v[42:45]
	v_mfma_i32_16x16x64_i8 v[38:41], v[136:139], v[206:209], v[38:41]
	v_mfma_i32_16x16x64_i8 v[34:37], v[158:161], v[206:209], v[34:37]
	v_mfma_i32_16x16x64_i8 v[62:65], v[140:143], v[186:189], v[62:65]
	v_mfma_i32_16x16x64_i8 v[58:61], v[162:165], v[186:189], v[58:61]
	v_mfma_i32_16x16x64_i8 v[54:57], v[140:143], v[194:197], v[54:57]
	v_mfma_i32_16x16x64_i8 v[50:53], v[162:165], v[194:197], v[50:53]
	v_mfma_i32_16x16x64_i8 v[46:49], v[140:143], v[202:205], v[46:49]
	v_mfma_i32_16x16x64_i8 v[42:45], v[162:165], v[202:205], v[42:45]
	v_mfma_i32_16x16x64_i8 v[38:41], v[140:143], v[210:213], v[38:41]
	v_mfma_i32_16x16x64_i8 v[34:37], v[162:165], v[210:213], v[34:37]
	s_setprio 0
	s_setprio 1
	v_mfma_i32_16x16x64_i8 v[30:33], v[166:169], v[182:185], v[30:33]
	v_mfma_i32_16x16x64_i8 v[26:29], v[174:177], v[182:185], v[26:29]
	v_mfma_i32_16x16x64_i8 v[22:25], v[166:169], v[190:193], v[22:25]
	v_mfma_i32_16x16x64_i8 v[18:21], v[174:177], v[190:193], v[18:21]
	v_mfma_i32_16x16x64_i8 v[14:17], v[166:169], v[198:201], v[14:17]
	v_mfma_i32_16x16x64_i8 v[10:13], v[174:177], v[198:201], v[10:13]
	v_mfma_i32_16x16x64_i8 v[6:9], v[166:169], v[206:209], v[6:9]
	v_mfma_i32_16x16x64_i8 v[2:5], v[174:177], v[206:209], v[2:5]
	v_mfma_i32_16x16x64_i8 v[30:33], v[170:173], v[186:189], v[30:33]
	v_mfma_i32_16x16x64_i8 v[26:29], v[178:181], v[186:189], v[26:29]
	v_mfma_i32_16x16x64_i8 v[22:25], v[170:173], v[194:197], v[22:25]
	v_mfma_i32_16x16x64_i8 v[18:21], v[178:181], v[194:197], v[18:21]
	v_mfma_i32_16x16x64_i8 v[14:17], v[170:173], v[202:205], v[14:17]
	v_mfma_i32_16x16x64_i8 v[10:13], v[178:181], v[202:205], v[10:13]
	v_mfma_i32_16x16x64_i8 v[6:9], v[170:173], v[210:213], v[6:9]
	v_mfma_i32_16x16x64_i8 v[2:5], v[178:181], v[210:213], v[2:5]
	s_setprio 0
	s_barrier
	s_add_i32 s65, s65, 2
	s_addk_i32 s63, 0x100
	s_addk_i32 s64, 0x100
	s_cmp_gt_u32 s65, 5
	s_cbranch_scc0 .LBB0_353
	s_and_b64 vcc, exec, s[24:25]
	s_cbranch_vccz .LBB0_356
	s_barrier

.LBB0_467:
	v_add_u32_e32 v147, 0x10000, v132
	ds_read_b128 v[138:141], v147
	ds_read_b128 v[142:145], v147 offset:1024
	ds_read_b128 v[148:151], v147 offset:2048
	ds_read_b128 v[152:155], v147 offset:3072
	v_add_u32_e32 v147, 0x14000, v132
	ds_read_b128 v[156:159], v147
	ds_read_b128 v[160:163], v147 offset:1024
	ds_read_b128 v[164:167], v147 offset:2048
	ds_read_b128 v[168:171], v147 offset:3072
	s_add_i32 s59, s3, s1
	s_add_i32 s58, s33, s1
	s_add_i32 s55, s59, 0x1600
	s_addk_i32 s58, 0x1600
	s_cmp_eq_u32 s1, 0
	s_cselect_b32 s60, s53, s55
	s_cselect_b32 s58, s54, s58
	s_add_i32 s55, s60, 0x80
	s_add_i32 s59, s59, 0xb1580
	s_mov_b32 m0, s46
	s_nop 0
	buffer_load_dwordx4 v130, s[12:15], s59 offen lds
	s_nop 0
	s_mov_b32 m0, s47
	s_nop 0
	buffer_load_dwordx4 v131, s[12:15], s59 offen lds
	ds_read_b128 v[172:175], v133
	ds_read_b128 v[176:179], v133 offset:1024
	ds_read_b128 v[180:183], v133 offset:2048
	ds_read_b128 v[184:187], v133 offset:3072
	ds_read_b128 v[188:191], v133 offset:4096
	ds_read_b128 v[192:195], v133 offset:5120
	ds_read_b128 v[196:199], v133 offset:6144
	ds_read_b128 v[200:203], v133 offset:7168
	s_waitcnt vmcnt(8)
	s_waitcnt lgkmcnt(0)
	s_barrier
	s_setprio 1
	s_waitcnt lgkmcnt(7)
	v_mfma_f32_16x16x32_bf16 v[134:137], v[138:141], v[172:175], v[134:137]
	v_mfma_f32_16x16x32_bf16 v[122:125], v[148:151], v[172:175], v[122:125]
	s_waitcnt lgkmcnt(5)
	v_mfma_f32_16x16x32_bf16 v[110:113], v[138:141], v[180:183], v[110:113]
	v_mfma_f32_16x16x32_bf16 v[106:109], v[148:151], v[180:183], v[106:109]
	s_waitcnt lgkmcnt(3)
	v_mfma_f32_16x16x32_bf16 v[94:97], v[138:141], v[188:191], v[94:97]
	v_mfma_f32_16x16x32_bf16 v[90:93], v[148:151], v[188:191], v[90:93]
	s_waitcnt lgkmcnt(1)
	v_mfma_f32_16x16x32_bf16 v[78:81], v[138:141], v[196:199], v[78:81]
	v_mfma_f32_16x16x32_bf16 v[74:77], v[148:151], v[196:199], v[74:77]
	v_mfma_f32_16x16x32_bf16 v[134:137], v[142:145], v[176:179], v[134:137]
	v_mfma_f32_16x16x32_bf16 v[122:125], v[152:155], v[176:179], v[122:125]
	v_mfma_f32_16x16x32_bf16 v[110:113], v[142:145], v[184:187], v[110:113]
	v_mfma_f32_16x16x32_bf16 v[106:109], v[152:155], v[184:187], v[106:109]
	v_mfma_f32_16x16x32_bf16 v[94:97], v[142:145], v[192:195], v[94:97]
	v_mfma_f32_16x16x32_bf16 v[90:93], v[152:155], v[192:195], v[90:93]
	s_waitcnt lgkmcnt(0)
	v_mfma_f32_16x16x32_bf16 v[78:81], v[142:145], v[200:203], v[78:81]
	v_mfma_f32_16x16x32_bf16 v[74:77], v[152:155], v[200:203], v[74:77]
	s_setprio 0
	s_setprio 1
	v_mfma_f32_16x16x32_bf16 v[118:121], v[156:159], v[172:175], v[118:121]
	v_mfma_f32_16x16x32_bf16 v[114:117], v[164:167], v[172:175], v[114:117]
	v_mfma_f32_16x16x32_bf16 v[102:105], v[156:159], v[180:183], v[102:105]
	v_mfma_f32_16x16x32_bf16 v[98:101], v[164:167], v[180:183], v[98:101]
	v_mfma_f32_16x16x32_bf16 v[86:89], v[156:159], v[188:191], v[86:89]
	v_mfma_f32_16x16x32_bf16 v[82:85], v[164:167], v[188:191], v[82:85]
	v_mfma_f32_16x16x32_bf16 v[70:73], v[156:159], v[196:199], v[70:73]
	v_mfma_f32_16x16x32_bf16 v[66:69], v[164:167], v[196:199], v[66:69]
	v_mfma_f32_16x16x32_bf16 v[118:121], v[160:163], v[176:179], v[118:121]
	v_mfma_f32_16x16x32_bf16 v[114:117], v[168:171], v[176:179], v[114:117]
	v_mfma_f32_16x16x32_bf16 v[102:105], v[160:163], v[184:187], v[102:105]
	v_mfma_f32_16x16x32_bf16 v[98:101], v[168:171], v[184:187], v[98:101]
	v_mfma_f32_16x16x32_bf16 v[86:89], v[160:163], v[192:195], v[86:89]
	v_mfma_f32_16x16x32_bf16 v[82:85], v[168:171], v[192:195], v[82:85]
	v_mfma_f32_16x16x32_bf16 v[70:73], v[160:163], v[200:203], v[70:73]
	v_mfma_f32_16x16x32_bf16 v[66:69], v[168:171], v[200:203], v[66:69]
	s_setprio 0
	s_barrier
	ds_read_b128 v[172:175], v133 offset:16384
	ds_read_b128 v[176:179], v133 offset:17408
	s_mov_b32 m0, s29
	s_nop 0
	buffer_load_dwordx4 v130, s[8:11], s58 offen lds
	ds_read_b128 v[180:183], v133 offset:18432
	ds_read_b128 v[184:187], v133 offset:19456
	s_add_i32 s59, s58, 0xb0000
	s_mov_b32 m0, s34
	s_nop 0
	buffer_load_dwordx4 v131, s[8:11], s58 offen lds
	ds_read_b128 v[188:191], v133 offset:20480
	ds_read_b128 v[192:195], v133 offset:21504
	s_nop 0
	s_mov_b32 m0, s35
	s_nop 0
	buffer_load_dwordx4 v130, s[8:11], s59 offen lds
	ds_read_b128 v[196:199], v133 offset:22528
	ds_read_b128 v[200:203], v133 offset:23552
	s_nop 0
	s_mov_b32 m0, s36
	s_nop 0
	buffer_load_dwordx4 v131, s[8:11], s59 offen lds
	s_nop 0
	s_mov_b32 m0, s28
	s_nop 0
	buffer_load_dwordx4 v130, s[12:15], s60 offen lds
	s_nop 0
	s_mov_b32 m0, s37
	s_nop 0
	buffer_load_dwordx4 v131, s[12:15], s60 offen lds
	s_waitcnt vmcnt(8)
	s_waitcnt lgkmcnt(0)
	s_barrier
	s_setprio 1
	s_waitcnt lgkmcnt(7)
	v_mfma_f32_16x16x32_bf16 v[62:65], v[138:141], v[172:175], v[62:65]
	v_mfma_f32_16x16x32_bf16 v[58:61], v[148:151], v[172:175], v[58:61]
	s_waitcnt lgkmcnt(5)
	v_mfma_f32_16x16x32_bf16 v[46:49], v[138:141], v[180:183], v[46:49]
	v_mfma_f32_16x16x32_bf16 v[42:45], v[148:151], v[180:183], v[42:45]
	s_waitcnt lgkmcnt(3)
	v_mfma_f32_16x16x32_bf16 v[30:33], v[138:141], v[188:191], v[30:33]
	v_mfma_f32_16x16x32_bf16 v[26:29], v[148:151], v[188:191], v[26:29]
	s_waitcnt lgkmcnt(1)
	v_mfma_f32_16x16x32_bf16 v[14:17], v[138:141], v[196:199], v[14:17]
	v_mfma_f32_16x16x32_bf16 v[10:13], v[148:151], v[196:199], v[10:13]
	v_mfma_f32_16x16x32_bf16 v[62:65], v[142:145], v[176:179], v[62:65]
	v_mfma_f32_16x16x32_bf16 v[58:61], v[152:155], v[176:179], v[58:61]
	v_mfma_f32_16x16x32_bf16 v[46:49], v[142:145], v[184:187], v[46:49]
	v_mfma_f32_16x16x32_bf16 v[42:45], v[152:155], v[184:187], v[42:45]
	v_mfma_f32_16x16x32_bf16 v[30:33], v[142:145], v[192:195], v[30:33]
	v_mfma_f32_16x16x32_bf16 v[26:29], v[152:155], v[192:195], v[26:29]
	s_waitcnt lgkmcnt(0)
	v_mfma_f32_16x16x32_bf16 v[14:17], v[142:145], v[200:203], v[14:17]
	v_mfma_f32_16x16x32_bf16 v[10:13], v[152:155], v[200:203], v[10:13]
	s_setprio 0
	s_setprio 1
	v_mfma_f32_16x16x32_bf16 v[54:57], v[156:159], v[172:175], v[54:57]
	v_mfma_f32_16x16x32_bf16 v[50:53], v[164:167], v[172:175], v[50:53]
	v_mfma_f32_16x16x32_bf16 v[38:41], v[156:159], v[180:183], v[38:41]
	v_mfma_f32_16x16x32_bf16 v[34:37], v[164:167], v[180:183], v[34:37]
	v_mfma_f32_16x16x32_bf16 v[22:25], v[156:159], v[188:191], v[22:25]
	v_mfma_f32_16x16x32_bf16 v[18:21], v[164:167], v[188:191], v[18:21]
	v_mfma_f32_16x16x32_bf16 v[6:9], v[156:159], v[196:199], v[6:9]
	v_mfma_f32_16x16x32_bf16 v[2:5], v[164:167], v[196:199], v[2:5]
	v_mfma_f32_16x16x32_bf16 v[54:57], v[160:163], v[176:179], v[54:57]
	v_mfma_f32_16x16x32_bf16 v[50:53], v[168:171], v[176:179], v[50:53]
	v_mfma_f32_16x16x32_bf16 v[38:41], v[160:163], v[184:187], v[38:41]
	v_mfma_f32_16x16x32_bf16 v[34:37], v[168:171], v[184:187], v[34:37]
	v_mfma_f32_16x16x32_bf16 v[22:25], v[160:163], v[192:195], v[22:25]
	v_mfma_f32_16x16x32_bf16 v[18:21], v[168:171], v[192:195], v[18:21]
	v_mfma_f32_16x16x32_bf16 v[6:9], v[160:163], v[200:203], v[6:9]
	v_mfma_f32_16x16x32_bf16 v[2:5], v[168:171], v[200:203], v[2:5]
	s_setprio 0
	s_barrier
	v_add_u32_e32 v147, 0x18000, v132
	ds_read_b128 v[138:141], v147
	ds_read_b128 v[142:145], v147 offset:1024
	ds_read_b128 v[148:151], v147 offset:2048
	ds_read_b128 v[152:155], v147 offset:3072
	v_add_u32_e32 v147, 0x1c000, v132
	ds_read_b128 v[156:159], v147
	ds_read_b128 v[160:163], v147 offset:1024
	ds_read_b128 v[164:167], v147 offset:2048
	ds_read_b128 v[168:171], v147 offset:3072
	s_add_i32 s59, s60, 0xb0000
	s_mov_b32 m0, s38
	s_nop 0
	buffer_load_dwordx4 v130, s[12:15], s59 offen lds
	s_nop 0
	s_mov_b32 m0, s39
	s_nop 0
	buffer_load_dwordx4 v131, s[12:15], s59 offen lds
	ds_read_b128 v[172:175], v133 offset:32768
	ds_read_b128 v[176:179], v133 offset:33792
	ds_read_b128 v[180:183], v133 offset:34816
	ds_read_b128 v[184:187], v133 offset:35840
	ds_read_b128 v[188:191], v133 offset:36864
	ds_read_b128 v[192:195], v133 offset:37888
	ds_read_b128 v[196:199], v133 offset:38912
	ds_read_b128 v[200:203], v133 offset:39936
	s_waitcnt vmcnt(8)
	s_waitcnt lgkmcnt(0)
	s_barrier
	s_setprio 1
	s_waitcnt lgkmcnt(7)
	v_mfma_f32_16x16x32_bf16 v[134:137], v[138:141], v[172:175], v[134:137]
	v_mfma_f32_16x16x32_bf16 v[122:125], v[148:151], v[172:175], v[122:125]
	s_waitcnt lgkmcnt(5)
	v_mfma_f32_16x16x32_bf16 v[110:113], v[138:141], v[180:183], v[110:113]
	v_mfma_f32_16x16x32_bf16 v[106:109], v[148:151], v[180:183], v[106:109]
	s_waitcnt lgkmcnt(3)
	v_mfma_f32_16x16x32_bf16 v[94:97], v[138:141], v[188:191], v[94:97]
	v_mfma_f32_16x16x32_bf16 v[90:93], v[148:151], v[188:191], v[90:93]
	s_waitcnt lgkmcnt(1)
	v_mfma_f32_16x16x32_bf16 v[78:81], v[138:141], v[196:199], v[78:81]
	v_mfma_f32_16x16x32_bf16 v[74:77], v[148:151], v[196:199], v[74:77]
	v_mfma_f32_16x16x32_bf16 v[134:137], v[142:145], v[176:179], v[134:137]
	v_mfma_f32_16x16x32_bf16 v[122:125], v[152:155], v[176:179], v[122:125]
	v_mfma_f32_16x16x32_bf16 v[110:113], v[142:145], v[184:187], v[110:113]
	v_mfma_f32_16x16x32_bf16 v[106:109], v[152:155], v[184:187], v[106:109]
	v_mfma_f32_16x16x32_bf16 v[94:97], v[142:145], v[192:195], v[94:97]
	v_mfma_f32_16x16x32_bf16 v[90:93], v[152:155], v[192:195], v[90:93]
	s_waitcnt lgkmcnt(0)
	v_mfma_f32_16x16x32_bf16 v[78:81], v[142:145], v[200:203], v[78:81]
	v_mfma_f32_16x16x32_bf16 v[74:77], v[152:155], v[200:203], v[74:77]
	s_setprio 0
	s_setprio 1
	v_mfma_f32_16x16x32_bf16 v[118:121], v[156:159], v[172:175], v[118:121]
	v_mfma_f32_16x16x32_bf16 v[114:117], v[164:167], v[172:175], v[114:117]
	v_mfma_f32_16x16x32_bf16 v[102:105], v[156:159], v[180:183], v[102:105]
	v_mfma_f32_16x16x32_bf16 v[98:101], v[164:167], v[180:183], v[98:101]
	v_mfma_f32_16x16x32_bf16 v[86:89], v[156:159], v[188:191], v[86:89]
	v_mfma_f32_16x16x32_bf16 v[82:85], v[164:167], v[188:191], v[82:85]
	v_mfma_f32_16x16x32_bf16 v[70:73], v[156:159], v[196:199], v[70:73]
	v_mfma_f32_16x16x32_bf16 v[66:69], v[164:167], v[196:199], v[66:69]
	v_mfma_f32_16x16x32_bf16 v[118:121], v[160:163], v[176:179], v[118:121]
	v_mfma_f32_16x16x32_bf16 v[114:117], v[168:171], v[176:179], v[114:117]
	v_mfma_f32_16x16x32_bf16 v[102:105], v[160:163], v[184:187], v[102:105]
	v_mfma_f32_16x16x32_bf16 v[98:101], v[168:171], v[184:187], v[98:101]
	v_mfma_f32_16x16x32_bf16 v[86:89], v[160:163], v[192:195], v[86:89]
	v_mfma_f32_16x16x32_bf16 v[82:85], v[168:171], v[192:195], v[82:85]
	v_mfma_f32_16x16x32_bf16 v[70:73], v[160:163], v[200:203], v[70:73]
	v_mfma_f32_16x16x32_bf16 v[66:69], v[168:171], v[200:203], v[66:69]
	s_setprio 0
	s_barrier
	ds_read_b128 v[172:175], v133 offset:49152
	ds_read_b128 v[176:179], v133 offset:50176
	s_add_i32 s59, s58, 0x80
	s_mov_b32 m0, s40
	s_nop 0
	buffer_load_dwordx4 v130, s[8:11], s59 offen lds
	ds_read_b128 v[180:183], v133 offset:51200
	ds_read_b128 v[184:187], v133 offset:52224
	s_add_i32 s58, s58, 0xb0080
	s_mov_b32 m0, s41
	s_nop 0
	buffer_load_dwordx4 v131, s[8:11], s59 offen lds
	ds_read_b128 v[188:191], v133 offset:53248
	ds_read_b128 v[192:195], v133 offset:54272
	s_nop 0
	s_mov_b32 m0, s44
	s_nop 0
	buffer_load_dwordx4 v130, s[8:11], s58 offen lds
	ds_read_b128 v[196:199], v133 offset:55296
	ds_read_b128 v[200:203], v133 offset:56320
	s_nop 0
	s_mov_b32 m0, s45
	s_nop 0
	buffer_load_dwordx4 v131, s[8:11], s58 offen lds
	s_nop 0
	s_mov_b32 m0, s42
	s_nop 0
	buffer_load_dwordx4 v130, s[12:15], s55 offen lds
	s_nop 0
	s_mov_b32 m0, s43
	s_nop 0
	buffer_load_dwordx4 v131, s[12:15], s55 offen lds
	s_waitcnt vmcnt(8)
	s_waitcnt lgkmcnt(0)
	s_barrier
	s_setprio 1
	s_waitcnt lgkmcnt(7)
	v_mfma_f32_16x16x32_bf16 v[62:65], v[138:141], v[172:175], v[62:65]
	v_mfma_f32_16x16x32_bf16 v[58:61], v[148:151], v[172:175], v[58:61]
	s_waitcnt lgkmcnt(5)
	v_mfma_f32_16x16x32_bf16 v[46:49], v[138:141], v[180:183], v[46:49]
	v_mfma_f32_16x16x32_bf16 v[42:45], v[148:151], v[180:183], v[42:45]
	s_waitcnt lgkmcnt(3)
	v_mfma_f32_16x16x32_bf16 v[30:33], v[138:141], v[188:191], v[30:33]
	v_mfma_f32_16x16x32_bf16 v[26:29], v[148:151], v[188:191], v[26:29]
	s_waitcnt lgkmcnt(1)
	v_mfma_f32_16x16x32_bf16 v[14:17], v[138:141], v[196:199], v[14:17]
	v_mfma_f32_16x16x32_bf16 v[10:13], v[148:151], v[196:199], v[10:13]
	v_mfma_f32_16x16x32_bf16 v[62:65], v[142:145], v[176:179], v[62:65]
	v_mfma_f32_16x16x32_bf16 v[58:61], v[152:155], v[176:179], v[58:61]
	v_mfma_f32_16x16x32_bf16 v[46:49], v[142:145], v[184:187], v[46:49]
	v_mfma_f32_16x16x32_bf16 v[42:45], v[152:155], v[184:187], v[42:45]
	v_mfma_f32_16x16x32_bf16 v[30:33], v[142:145], v[192:195], v[30:33]
	v_mfma_f32_16x16x32_bf16 v[26:29], v[152:155], v[192:195], v[26:29]
	s_waitcnt lgkmcnt(0)
	v_mfma_f32_16x16x32_bf16 v[14:17], v[142:145], v[200:203], v[14:17]
	v_mfma_f32_16x16x32_bf16 v[10:13], v[152:155], v[200:203], v[10:13]
	s_setprio 0
	s_setprio 1
	v_mfma_f32_16x16x32_bf16 v[54:57], v[156:159], v[172:175], v[54:57]
	v_mfma_f32_16x16x32_bf16 v[50:53], v[164:167], v[172:175], v[50:53]
	v_mfma_f32_16x16x32_bf16 v[38:41], v[156:159], v[180:183], v[38:41]
	v_mfma_f32_16x16x32_bf16 v[34:37], v[164:167], v[180:183], v[34:37]
	v_mfma_f32_16x16x32_bf16 v[22:25], v[156:159], v[188:191], v[22:25]
	v_mfma_f32_16x16x32_bf16 v[18:21], v[164:167], v[188:191], v[18:21]
	v_mfma_f32_16x16x32_bf16 v[6:9], v[156:159], v[196:199], v[6:9]
	v_mfma_f32_16x16x32_bf16 v[2:5], v[164:167], v[196:199], v[2:5]
	v_mfma_f32_16x16x32_bf16 v[54:57], v[160:163], v[176:179], v[54:57]
	v_mfma_f32_16x16x32_bf16 v[50:53], v[168:171], v[176:179], v[50:53]
	v_mfma_f32_16x16x32_bf16 v[38:41], v[160:163], v[184:187], v[38:41]
	v_mfma_f32_16x16x32_bf16 v[34:37], v[168:171], v[184:187], v[34:37]
	v_mfma_f32_16x16x32_bf16 v[22:25], v[160:163], v[192:195], v[22:25]
	v_mfma_f32_16x16x32_bf16 v[18:21], v[168:171], v[192:195], v[18:21]
	v_mfma_f32_16x16x32_bf16 v[6:9], v[160:163], v[200:203], v[6:9]
	v_mfma_f32_16x16x32_bf16 v[2:5], v[168:171], v[200:203], v[2:5]
	s_setprio 0
	s_barrier
	s_add_i32 s0, s0, 2
	s_addk_i32 s1, 0x100
	s_cmp_gt_u32 s0, 41
	s_cbranch_scc0 .LBB0_467
	s_andn2_b64 vcc, exec, s[6:7]
	s_cbranch_vccnz .LBB0_455
	v_mov_b32_e32 v2, 0
	s_mov_b32 s18, s50
	s_mov_b32 s31, s51
	s_mov_b32 s33, s54
	s_mov_b32 s3, s53
	s_mov_b32 s49, s52
	v_mov_b32_e32 v3, v2
	v_mov_b32_e32 v4, v2
	v_mov_b32_e32 v5, v2
	v_mov_b32_e32 v6, v2
	v_mov_b32_e32 v7, v2
	v_mov_b32_e32 v8, v2
	v_mov_b32_e32 v9, v2
	v_mov_b32_e32 v18, v2
	v_mov_b32_e32 v19, v2
	v_mov_b32_e32 v20, v2
	v_mov_b32_e32 v21, v2
	v_mov_b32_e32 v22, v2
	v_mov_b32_e32 v23, v2
	v_mov_b32_e32 v24, v2
	v_mov_b32_e32 v25, v2
	v_mov_b32_e32 v34, v2
	v_mov_b32_e32 v35, v2
	v_mov_b32_e32 v36, v2
	v_mov_b32_e32 v37, v2
	v_mov_b32_e32 v38, v2
	v_mov_b32_e32 v39, v2
	v_mov_b32_e32 v40, v2
	v_mov_b32_e32 v41, v2
	v_mov_b32_e32 v50, v2
	v_mov_b32_e32 v51, v2
	v_mov_b32_e32 v52, v2
	v_mov_b32_e32 v53, v2
	v_mov_b32_e32 v54, v2
	v_mov_b32_e32 v55, v2
	v_mov_b32_e32 v56, v2
	v_mov_b32_e32 v57, v2
	v_mov_b32_e32 v10, v2
	v_mov_b32_e32 v11, v2
	v_mov_b32_e32 v12, v2
	v_mov_b32_e32 v13, v2
	v_mov_b32_e32 v14, v2
	v_mov_b32_e32 v15, v2
	v_mov_b32_e32 v16, v2
	v_mov_b32_e32 v17, v2
	v_mov_b32_e32 v26, v2
	v_mov_b32_e32 v27, v2
	v_mov_b32_e32 v28, v2
	v_mov_b32_e32 v29, v2
	v_mov_b32_e32 v30, v2
	v_mov_b32_e32 v31, v2
	v_mov_b32_e32 v32, v2
	v_mov_b32_e32 v33, v2
	v_mov_b32_e32 v42, v2
	v_mov_b32_e32 v43, v2
	v_mov_b32_e32 v44, v2
	v_mov_b32_e32 v45, v2
	v_mov_b32_e32 v46, v2
	v_mov_b32_e32 v47, v2
	v_mov_b32_e32 v48, v2
	v_mov_b32_e32 v49, v2
	v_mov_b32_e32 v58, v2
	v_mov_b32_e32 v59, v2
	v_mov_b32_e32 v60, v2
	v_mov_b32_e32 v61, v2
	v_mov_b32_e32 v62, v2
	v_mov_b32_e32 v63, v2
	v_mov_b32_e32 v64, v2
	v_mov_b32_e32 v65, v2
	v_mov_b32_e32 v66, v2
	v_mov_b32_e32 v67, v2
	v_mov_b32_e32 v68, v2
	v_mov_b32_e32 v69, v2
	v_mov_b32_e32 v70, v2
	v_mov_b32_e32 v71, v2
	v_mov_b32_e32 v72, v2
	v_mov_b32_e32 v73, v2
	v_mov_b32_e32 v82, v2
	v_mov_b32_e32 v83, v2
	v_mov_b32_e32 v84, v2
	v_mov_b32_e32 v85, v2
	v_mov_b32_e32 v86, v2
	v_mov_b32_e32 v87, v2
	v_mov_b32_e32 v88, v2
	v_mov_b32_e32 v89, v2
	v_mov_b32_e32 v98, v2
	v_mov_b32_e32 v99, v2
	v_mov_b32_e32 v100, v2
	v_mov_b32_e32 v101, v2
	v_mov_b32_e32 v102, v2
	v_mov_b32_e32 v103, v2
	v_mov_b32_e32 v104, v2
	v_mov_b32_e32 v105, v2
	v_mov_b32_e32 v114, v2
	v_mov_b32_e32 v115, v2
	v_mov_b32_e32 v116, v2
	v_mov_b32_e32 v117, v2
	v_mov_b32_e32 v118, v2
	v_mov_b32_e32 v119, v2
	v_mov_b32_e32 v120, v2
	v_mov_b32_e32 v121, v2
	v_mov_b32_e32 v74, v2
	v_mov_b32_e32 v75, v2
	v_mov_b32_e32 v76, v2
	v_mov_b32_e32 v77, v2
	v_mov_b32_e32 v78, v2
	v_mov_b32_e32 v79, v2
	v_mov_b32_e32 v80, v2
	v_mov_b32_e32 v81, v2
	v_mov_b32_e32 v90, v2
	v_mov_b32_e32 v91, v2
	v_mov_b32_e32 v92, v2
	v_mov_b32_e32 v93, v2
	v_mov_b32_e32 v94, v2
	v_mov_b32_e32 v95, v2
	v_mov_b32_e32 v96, v2
	v_mov_b32_e32 v97, v2
	v_mov_b32_e32 v106, v2
	v_mov_b32_e32 v107, v2
	v_mov_b32_e32 v108, v2
	v_mov_b32_e32 v109, v2
	v_mov_b32_e32 v110, v2
	v_mov_b32_e32 v111, v2
	v_mov_b32_e32 v112, v2
	v_mov_b32_e32 v113, v2
	v_mov_b32_e32 v122, v2
	v_mov_b32_e32 v123, v2
	v_mov_b32_e32 v124, v2
	v_mov_b32_e32 v125, v2
	v_mov_b32_e32 v134, v2
	v_mov_b32_e32 v135, v2
	v_mov_b32_e32 v136, v2
	v_mov_b32_e32 v137, v2
	s_branch .LBB0_455

.LBB0_619:
	ds_read_b128 v[38:41], v210
	ds_read_b128 v[42:45], v210 offset:1024
	ds_read_b128 v[46:49], v210 offset:2048
	ds_read_b128 v[58:61], v210 offset:3072
	ds_read_b128 v[142:145], v211
	ds_read_b128 v[146:149], v211 offset:1024
	ds_read_b128 v[150:153], v211 offset:2048
	ds_read_b128 v[154:157], v211 offset:3072
	s_add_i32 s6, s1, 0xfffe0080
	s_cmp_eq_u32 s3, 4
	s_cselect_b32 s8, s75, s6
	s_cselect_b32 s7, s0, s2
	s_add_i32 s6, s8, 0x80
	s_mov_b32 m0, s68
	s_nop 0
	buffer_load_dwordx4 v206, s[16:19], s1 offen lds
	s_nop 0
	s_mov_b32 m0, s69
	s_nop 0
	buffer_load_dwordx4 v207, s[16:19], s1 offen lds
	ds_read_b128 v[166:169], v212
	ds_read_b128 v[170:173], v212 offset:1024
	ds_read_b128 v[174:177], v212 offset:2048
	ds_read_b128 v[178:181], v212 offset:3072
	ds_read_b128 v[190:193], v212 offset:4096
	ds_read_b128 v[194:197], v212 offset:5120
	ds_read_b128 v[198:201], v212 offset:6144
	ds_read_b128 v[216:219], v212 offset:7168
	s_waitcnt vmcnt(8)
	s_waitcnt lgkmcnt(0)
	s_barrier
	s_setprio 1
	s_waitcnt lgkmcnt(7)
	v_mfma_i32_16x16x64_i8 v[162:165], v[38:41], v[166:169], v[162:165]
	v_mfma_i32_16x16x64_i8 v[158:161], v[46:49], v[166:169], v[158:161]
	s_waitcnt lgkmcnt(5)
	v_mfma_i32_16x16x64_i8 v[130:133], v[38:41], v[174:177], v[130:133]
	v_mfma_i32_16x16x64_i8 v[126:129], v[46:49], v[174:177], v[126:129]
	s_waitcnt lgkmcnt(3)
	v_mfma_i32_16x16x64_i8 v[114:117], v[38:41], v[190:193], v[114:117]
	v_mfma_i32_16x16x64_i8 v[110:113], v[46:49], v[190:193], v[110:113]
	s_waitcnt lgkmcnt(1)
	v_mfma_i32_16x16x64_i8 v[98:101], v[38:41], v[198:201], v[98:101]
	v_mfma_i32_16x16x64_i8 v[94:97], v[46:49], v[198:201], v[94:97]
	v_mfma_i32_16x16x64_i8 v[162:165], v[42:45], v[170:173], v[162:165]
	v_mfma_i32_16x16x64_i8 v[158:161], v[58:61], v[170:173], v[158:161]
	v_mfma_i32_16x16x64_i8 v[130:133], v[42:45], v[178:181], v[130:133]
	v_mfma_i32_16x16x64_i8 v[126:129], v[58:61], v[178:181], v[126:129]
	v_mfma_i32_16x16x64_i8 v[114:117], v[42:45], v[194:197], v[114:117]
	v_mfma_i32_16x16x64_i8 v[110:113], v[58:61], v[194:197], v[110:113]
	s_waitcnt lgkmcnt(0)
	v_mfma_i32_16x16x64_i8 v[98:101], v[42:45], v[216:219], v[98:101]
	v_mfma_i32_16x16x64_i8 v[94:97], v[58:61], v[216:219], v[94:97]
	s_setprio 0
	s_setprio 1
	v_mfma_i32_16x16x64_i8 v[138:141], v[142:145], v[166:169], v[138:141]
	v_mfma_i32_16x16x64_i8 v[134:137], v[150:153], v[166:169], v[134:137]
	v_mfma_i32_16x16x64_i8 v[122:125], v[142:145], v[174:177], v[122:125]
	v_mfma_i32_16x16x64_i8 v[118:121], v[150:153], v[174:177], v[118:121]
	v_mfma_i32_16x16x64_i8 v[106:109], v[142:145], v[190:193], v[106:109]
	v_mfma_i32_16x16x64_i8 v[102:105], v[150:153], v[190:193], v[102:105]
	v_mfma_i32_16x16x64_i8 v[90:93], v[142:145], v[198:201], v[90:93]
	v_mfma_i32_16x16x64_i8 v[86:89], v[150:153], v[198:201], v[86:89]
	v_mfma_i32_16x16x64_i8 v[138:141], v[146:149], v[170:173], v[138:141]
	v_mfma_i32_16x16x64_i8 v[134:137], v[154:157], v[170:173], v[134:137]
	v_mfma_i32_16x16x64_i8 v[122:125], v[146:149], v[178:181], v[122:125]
	v_mfma_i32_16x16x64_i8 v[118:121], v[154:157], v[178:181], v[118:121]
	v_mfma_i32_16x16x64_i8 v[106:109], v[146:149], v[194:197], v[106:109]
	v_mfma_i32_16x16x64_i8 v[102:105], v[154:157], v[194:197], v[102:105]
	v_mfma_i32_16x16x64_i8 v[90:93], v[146:149], v[216:219], v[90:93]
	v_mfma_i32_16x16x64_i8 v[86:89], v[154:157], v[216:219], v[86:89]
	s_setprio 0
	s_barrier
	ds_read_b128 v[166:169], v212 offset:16384
	ds_read_b128 v[170:173], v212 offset:17408
	s_mov_b32 m0, s48
	s_nop 0
	buffer_load_dwordx4 v204, s[12:15], s7 offen lds
	ds_read_b128 v[174:177], v212 offset:18432
	ds_read_b128 v[178:181], v212 offset:19456
	s_add_i32 s9, s7, 0x20000
	s_mov_b32 m0, s49
	s_nop 0
	buffer_load_dwordx4 v205, s[12:15], s7 offen lds
	ds_read_b128 v[190:193], v212 offset:20480
	ds_read_b128 v[194:197], v212 offset:21504
	s_nop 0
	s_mov_b32 m0, s50
	s_nop 0
	buffer_load_dwordx4 v204, s[12:15], s9 offen lds
	ds_read_b128 v[198:201], v212 offset:22528
	ds_read_b128 v[216:219], v212 offset:23552
	s_nop 0
	s_mov_b32 m0, s51
	s_nop 0
	buffer_load_dwordx4 v205, s[12:15], s9 offen lds
	s_nop 0
	s_mov_b32 m0, s47
	s_nop 0
	buffer_load_dwordx4 v206, s[16:19], s8 offen lds
	s_nop 0
	s_mov_b32 m0, s52
	s_nop 0
	buffer_load_dwordx4 v207, s[16:19], s8 offen lds
	s_waitcnt vmcnt(8)
	s_waitcnt lgkmcnt(0)
	s_barrier
	s_setprio 1
	s_waitcnt lgkmcnt(7)
	v_mfma_i32_16x16x64_i8 v[82:85], v[38:41], v[166:169], v[82:85]
	v_mfma_i32_16x16x64_i8 v[78:81], v[46:49], v[166:169], v[78:81]
	s_waitcnt lgkmcnt(5)
	v_mfma_i32_16x16x64_i8 v[66:69], v[38:41], v[174:177], v[66:69]
	v_mfma_i32_16x16x64_i8 v[62:65], v[46:49], v[174:177], v[62:65]
	s_waitcnt lgkmcnt(3)
	v_mfma_i32_16x16x64_i8 v[34:37], v[38:41], v[190:193], v[34:37]
	v_mfma_i32_16x16x64_i8 v[30:33], v[46:49], v[190:193], v[30:33]
	s_waitcnt lgkmcnt(1)
	v_mfma_i32_16x16x64_i8 v[18:21], v[38:41], v[198:201], v[18:21]
	v_mfma_i32_16x16x64_i8 v[14:17], v[46:49], v[198:201], v[14:17]
	v_mfma_i32_16x16x64_i8 v[82:85], v[42:45], v[170:173], v[82:85]
	v_mfma_i32_16x16x64_i8 v[78:81], v[58:61], v[170:173], v[78:81]
	v_mfma_i32_16x16x64_i8 v[66:69], v[42:45], v[178:181], v[66:69]
	v_mfma_i32_16x16x64_i8 v[62:65], v[58:61], v[178:181], v[62:65]
	v_mfma_i32_16x16x64_i8 v[34:37], v[42:45], v[194:197], v[34:37]
	v_mfma_i32_16x16x64_i8 v[30:33], v[58:61], v[194:197], v[30:33]
	s_waitcnt lgkmcnt(0)
	v_mfma_i32_16x16x64_i8 v[18:21], v[42:45], v[216:219], v[18:21]
	v_mfma_i32_16x16x64_i8 v[14:17], v[58:61], v[216:219], v[14:17]
	s_setprio 0
	s_setprio 1
	v_mfma_i32_16x16x64_i8 v[50:53], v[150:153], v[174:177], v[50:53]
	v_mfma_i32_16x16x64_i8 v[26:29], v[142:145], v[190:193], v[26:29]
	v_mfma_i32_16x16x64_i8 v[22:25], v[150:153], v[190:193], v[22:25]
	v_mfma_i32_16x16x64_i8 v[10:13], v[142:145], v[198:201], v[10:13]
	v_mfma_i32_16x16x64_i8 v[4:7], v[150:153], v[198:201], v[6:9]
	v_mfma_i32_16x16x64_i8 v[38:41], v[142:145], v[166:169], v[74:77]
	v_mfma_i32_16x16x64_i8 v[42:45], v[150:153], v[166:169], v[70:73]
	v_mfma_i32_16x16x64_i8 v[46:49], v[142:145], v[174:177], v[54:57]
	v_mfma_i32_16x16x64_i8 v[50:53], v[154:157], v[178:181], v[50:53]
	v_mfma_i32_16x16x64_i8 v[26:29], v[146:149], v[194:197], v[26:29]
	v_mfma_i32_16x16x64_i8 v[22:25], v[154:157], v[194:197], v[22:25]
	v_mfma_i32_16x16x64_i8 v[10:13], v[146:149], v[216:219], v[10:13]
	v_mfma_i32_16x16x64_i8 v[4:7], v[154:157], v[216:219], v[4:7]
	v_mfma_i32_16x16x64_i8 v[38:41], v[146:149], v[170:173], v[38:41]
	v_mfma_i32_16x16x64_i8 v[42:45], v[154:157], v[170:173], v[42:45]
	v_mfma_i32_16x16x64_i8 v[46:49], v[146:149], v[178:181], v[46:49]
	s_setprio 0
	s_barrier
	ds_read_b128 v[54:57], v213
	ds_read_b128 v[58:61], v213 offset:1024
	ds_read_b128 v[70:73], v213 offset:2048
	ds_read_b128 v[74:77], v213 offset:3072
	ds_read_b128 v[142:145], v214
	ds_read_b128 v[146:149], v214 offset:1024
	ds_read_b128 v[150:153], v214 offset:2048
	ds_read_b128 v[154:157], v214 offset:3072
	s_add_i32 s8, s8, 0x20000
	s_mov_b32 m0, s53
	s_nop 0
	buffer_load_dwordx4 v206, s[16:19], s8 offen lds
	s_nop 0
	s_mov_b32 m0, s54
	s_nop 0
	buffer_load_dwordx4 v207, s[16:19], s8 offen lds
	ds_read_b128 v[166:169], v212 offset:32768
	ds_read_b128 v[170:173], v212 offset:33792
	ds_read_b128 v[174:177], v212 offset:34816
	ds_read_b128 v[178:181], v212 offset:35840
	ds_read_b128 v[190:193], v212 offset:36864
	ds_read_b128 v[194:197], v212 offset:37888
	ds_read_b128 v[198:201], v212 offset:38912
	ds_read_b128 v[216:219], v212 offset:39936
	s_waitcnt vmcnt(8)
	s_waitcnt lgkmcnt(0)
	s_barrier
	s_setprio 1
	s_waitcnt lgkmcnt(7)
	v_mfma_i32_16x16x64_i8 v[162:165], v[54:57], v[166:169], v[162:165]
	v_mfma_i32_16x16x64_i8 v[158:161], v[70:73], v[166:169], v[158:161]
	s_waitcnt lgkmcnt(5)
	v_mfma_i32_16x16x64_i8 v[130:133], v[54:57], v[174:177], v[130:133]
	v_mfma_i32_16x16x64_i8 v[126:129], v[70:73], v[174:177], v[126:129]
	s_waitcnt lgkmcnt(3)
	v_mfma_i32_16x16x64_i8 v[114:117], v[54:57], v[190:193], v[114:117]
	v_mfma_i32_16x16x64_i8 v[110:113], v[70:73], v[190:193], v[110:113]
	s_waitcnt lgkmcnt(1)
	v_mfma_i32_16x16x64_i8 v[98:101], v[54:57], v[198:201], v[98:101]
	v_mfma_i32_16x16x64_i8 v[94:97], v[70:73], v[198:201], v[94:97]
	v_mfma_i32_16x16x64_i8 v[162:165], v[58:61], v[170:173], v[162:165]
	v_mfma_i32_16x16x64_i8 v[158:161], v[74:77], v[170:173], v[158:161]
	v_mfma_i32_16x16x64_i8 v[130:133], v[58:61], v[178:181], v[130:133]
	v_mfma_i32_16x16x64_i8 v[126:129], v[74:77], v[178:181], v[126:129]
	v_mfma_i32_16x16x64_i8 v[114:117], v[58:61], v[194:197], v[114:117]
	v_mfma_i32_16x16x64_i8 v[110:113], v[74:77], v[194:197], v[110:113]
	s_waitcnt lgkmcnt(0)
	v_mfma_i32_16x16x64_i8 v[98:101], v[58:61], v[216:219], v[98:101]
	v_mfma_i32_16x16x64_i8 v[94:97], v[74:77], v[216:219], v[94:97]
	s_setprio 0
	s_setprio 1
	v_mfma_i32_16x16x64_i8 v[138:141], v[142:145], v[166:169], v[138:141]
	v_mfma_i32_16x16x64_i8 v[134:137], v[150:153], v[166:169], v[134:137]
	v_mfma_i32_16x16x64_i8 v[122:125], v[142:145], v[174:177], v[122:125]
	v_mfma_i32_16x16x64_i8 v[118:121], v[150:153], v[174:177], v[118:121]
	v_mfma_i32_16x16x64_i8 v[106:109], v[142:145], v[190:193], v[106:109]
	v_mfma_i32_16x16x64_i8 v[102:105], v[150:153], v[190:193], v[102:105]
	v_mfma_i32_16x16x64_i8 v[90:93], v[142:145], v[198:201], v[90:93]
	v_mfma_i32_16x16x64_i8 v[86:89], v[150:153], v[198:201], v[86:89]
	v_mfma_i32_16x16x64_i8 v[138:141], v[146:149], v[170:173], v[138:141]
	v_mfma_i32_16x16x64_i8 v[134:137], v[154:157], v[170:173], v[134:137]
	v_mfma_i32_16x16x64_i8 v[122:125], v[146:149], v[178:181], v[122:125]
	v_mfma_i32_16x16x64_i8 v[118:121], v[154:157], v[178:181], v[118:121]
	v_mfma_i32_16x16x64_i8 v[106:109], v[146:149], v[194:197], v[106:109]
	v_mfma_i32_16x16x64_i8 v[102:105], v[154:157], v[194:197], v[102:105]
	v_mfma_i32_16x16x64_i8 v[90:93], v[146:149], v[216:219], v[90:93]
	v_mfma_i32_16x16x64_i8 v[86:89], v[154:157], v[216:219], v[86:89]
	s_setprio 0
	s_barrier
	ds_read_b128 v[166:169], v212 offset:49152
	ds_read_b128 v[170:173], v212 offset:50176
	s_or_b32 s8, s7, 0x80
	s_mov_b32 m0, s62
	s_nop 0
	buffer_load_dwordx4 v204, s[12:15], s8 offen lds
	ds_read_b128 v[174:177], v212 offset:51200
	ds_read_b128 v[178:181], v212 offset:52224
	s_add_i32 s7, s7, 0x20080
	s_mov_b32 m0, s63
	s_nop 0
	buffer_load_dwordx4 v205, s[12:15], s8 offen lds
	ds_read_b128 v[190:193], v212 offset:53248
	ds_read_b128 v[194:197], v212 offset:54272
	s_nop 0
	s_mov_b32 m0, s66
	s_nop 0
	buffer_load_dwordx4 v204, s[12:15], s7 offen lds
	ds_read_b128 v[198:201], v212 offset:55296
	ds_read_b128 v[216:219], v212 offset:56320
	s_nop 0
	s_mov_b32 m0, s67
	s_nop 0
	buffer_load_dwordx4 v205, s[12:15], s7 offen lds
	s_nop 0
	s_mov_b32 m0, s64
	s_nop 0
	buffer_load_dwordx4 v206, s[16:19], s6 offen lds
	s_nop 0
	s_mov_b32 m0, s65
	s_nop 0
	buffer_load_dwordx4 v207, s[16:19], s6 offen lds
	s_waitcnt vmcnt(8)
	s_waitcnt lgkmcnt(0)
	s_barrier
	s_setprio 1
	s_waitcnt lgkmcnt(7)
	v_mfma_i32_16x16x64_i8 v[82:85], v[54:57], v[166:169], v[82:85]
	v_mfma_i32_16x16x64_i8 v[78:81], v[70:73], v[166:169], v[78:81]
	s_waitcnt lgkmcnt(5)
	v_mfma_i32_16x16x64_i8 v[66:69], v[54:57], v[174:177], v[66:69]
	v_mfma_i32_16x16x64_i8 v[62:65], v[70:73], v[174:177], v[62:65]
	s_waitcnt lgkmcnt(3)
	v_mfma_i32_16x16x64_i8 v[34:37], v[54:57], v[190:193], v[34:37]
	v_mfma_i32_16x16x64_i8 v[30:33], v[70:73], v[190:193], v[30:33]
	s_waitcnt lgkmcnt(1)
	v_mfma_i32_16x16x64_i8 v[18:21], v[54:57], v[198:201], v[18:21]
	v_mfma_i32_16x16x64_i8 v[14:17], v[70:73], v[198:201], v[14:17]
	v_mfma_i32_16x16x64_i8 v[82:85], v[58:61], v[170:173], v[82:85]
	v_mfma_i32_16x16x64_i8 v[78:81], v[74:77], v[170:173], v[78:81]
	v_mfma_i32_16x16x64_i8 v[66:69], v[58:61], v[178:181], v[66:69]
	v_mfma_i32_16x16x64_i8 v[62:65], v[74:77], v[178:181], v[62:65]
	v_mfma_i32_16x16x64_i8 v[34:37], v[58:61], v[194:197], v[34:37]
	v_mfma_i32_16x16x64_i8 v[30:33], v[74:77], v[194:197], v[30:33]
	s_waitcnt lgkmcnt(0)
	v_mfma_i32_16x16x64_i8 v[18:21], v[58:61], v[216:219], v[18:21]
	v_mfma_i32_16x16x64_i8 v[14:17], v[74:77], v[216:219], v[14:17]
	s_setprio 0
	s_setprio 1
	v_mfma_i32_16x16x64_i8 v[38:41], v[142:145], v[166:169], v[38:41]
	v_mfma_i32_16x16x64_i8 v[74:77], v[146:149], v[170:173], v[38:41]
	v_mfma_i32_16x16x64_i8 v[38:41], v[150:153], v[166:169], v[42:45]
	v_mfma_i32_16x16x64_i8 v[70:73], v[154:157], v[170:173], v[38:41]
	v_mfma_i32_16x16x64_i8 v[38:41], v[142:145], v[174:177], v[46:49]
	v_mfma_i32_16x16x64_i8 v[54:57], v[146:149], v[178:181], v[38:41]
	v_mfma_i32_16x16x64_i8 v[38:41], v[150:153], v[174:177], v[50:53]
	v_mfma_i32_16x16x64_i8 v[26:29], v[142:145], v[190:193], v[26:29]
	v_mfma_i32_16x16x64_i8 v[22:25], v[150:153], v[190:193], v[22:25]
	v_mfma_i32_16x16x64_i8 v[8:11], v[142:145], v[198:201], v[10:13]
	v_mfma_i32_16x16x64_i8 v[4:7], v[150:153], v[198:201], v[4:7]
	v_mfma_i32_16x16x64_i8 v[50:53], v[154:157], v[178:181], v[38:41]
	v_mfma_i32_16x16x64_i8 v[26:29], v[146:149], v[194:197], v[26:29]
	v_mfma_i32_16x16x64_i8 v[22:25], v[154:157], v[194:197], v[22:25]
	v_mfma_i32_16x16x64_i8 v[10:13], v[146:149], v[216:219], v[8:11]
	v_mfma_i32_16x16x64_i8 v[6:9], v[154:157], v[216:219], v[4:7]
	s_setprio 0
	s_barrier
	s_add_i32 s3, s3, 2
	s_addk_i32 s1, 0x100
	s_addk_i32 s2, 0x100
	s_cmp_gt_u32 s3, 5
	s_cbranch_scc0 .LBB0_619
	s_and_b64 vcc, exec, s[34:35]
	s_cbranch_vccz .LBB0_622
	s_barrier

.LBB0_943:
	v_add_u32_e32 v150, 0x10000, v8
	v_add_u32_e32 v166, 0x14000, v8
	ds_read_b128 v[10:13], v150
	ds_read_b128 v[14:17], v150 offset:1024
	ds_read_b128 v[146:149], v150 offset:2048
	ds_read_b128 v[150:153], v150 offset:3072
	ds_read_b128 v[154:157], v166
	ds_read_b128 v[158:161], v166 offset:1024
	ds_read_b128 v[162:165], v166 offset:2048
	ds_read_b128 v[166:169], v166 offset:3072
	s_add_i32 s61, s37, s58
	s_add_i32 s60, s33, s58
	s_add_i32 s59, s61, 0x400
	s_addk_i32 s60, 0x400
	s_cmp_eq_u32 s58, 0
	s_cselect_b32 s62, s53, s59
	s_cselect_b32 s60, s54, s60
	s_or_b32 s59, s62, 0x80
	s_add_i32 s61, s61, 0x20380
	s_mov_b32 m0, s48
	s_nop 0
	buffer_load_dwordx4 v6, s[12:15], s61 offen lds
	s_nop 0
	s_mov_b32 m0, s49
	s_nop 0
	buffer_load_dwordx4 v7, s[12:15], s61 offen lds
	ds_read_b128 v[170:173], v9
	ds_read_b128 v[174:177], v9 offset:1024
	ds_read_b128 v[178:181], v9 offset:2048
	ds_read_b128 v[182:185], v9 offset:3072
	ds_read_b128 v[186:189], v9 offset:4096
	ds_read_b128 v[190:193], v9 offset:5120
	ds_read_b128 v[194:197], v9 offset:6144
	ds_read_b128 v[198:201], v9 offset:7168
	s_waitcnt vmcnt(8)
	s_waitcnt lgkmcnt(0)
	s_barrier
	s_setprio 1
	s_waitcnt lgkmcnt(7)
	v_mfma_i32_16x16x64_i8 v[142:145], v[10:13], v[170:173], v[142:145]
	v_mfma_i32_16x16x64_i8 v[138:141], v[146:149], v[170:173], v[138:141]
	s_waitcnt lgkmcnt(5)
	v_mfma_i32_16x16x64_i8 v[126:129], v[10:13], v[178:181], v[126:129]
	v_mfma_i32_16x16x64_i8 v[122:125], v[146:149], v[178:181], v[122:125]
	s_waitcnt lgkmcnt(3)
	v_mfma_i32_16x16x64_i8 v[110:113], v[10:13], v[186:189], v[110:113]
	v_mfma_i32_16x16x64_i8 v[106:109], v[146:149], v[186:189], v[106:109]
	s_waitcnt lgkmcnt(1)
	v_mfma_i32_16x16x64_i8 v[94:97], v[10:13], v[194:197], v[94:97]
	v_mfma_i32_16x16x64_i8 v[90:93], v[146:149], v[194:197], v[90:93]
	v_mfma_i32_16x16x64_i8 v[142:145], v[14:17], v[174:177], v[142:145]
	v_mfma_i32_16x16x64_i8 v[138:141], v[150:153], v[174:177], v[138:141]
	v_mfma_i32_16x16x64_i8 v[126:129], v[14:17], v[182:185], v[126:129]
	v_mfma_i32_16x16x64_i8 v[122:125], v[150:153], v[182:185], v[122:125]
	v_mfma_i32_16x16x64_i8 v[110:113], v[14:17], v[190:193], v[110:113]
	v_mfma_i32_16x16x64_i8 v[106:109], v[150:153], v[190:193], v[106:109]
	s_waitcnt lgkmcnt(0)
	v_mfma_i32_16x16x64_i8 v[94:97], v[14:17], v[198:201], v[94:97]
	v_mfma_i32_16x16x64_i8 v[90:93], v[150:153], v[198:201], v[90:93]
	s_setprio 0
	s_setprio 1
	v_mfma_i32_16x16x64_i8 v[134:137], v[154:157], v[170:173], v[134:137]
	v_mfma_i32_16x16x64_i8 v[130:133], v[162:165], v[170:173], v[130:133]
	v_mfma_i32_16x16x64_i8 v[118:121], v[154:157], v[178:181], v[118:121]
	v_mfma_i32_16x16x64_i8 v[114:117], v[162:165], v[178:181], v[114:117]
	v_mfma_i32_16x16x64_i8 v[102:105], v[154:157], v[186:189], v[102:105]
	v_mfma_i32_16x16x64_i8 v[98:101], v[162:165], v[186:189], v[98:101]
	v_mfma_i32_16x16x64_i8 v[86:89], v[154:157], v[194:197], v[86:89]
	v_mfma_i32_16x16x64_i8 v[82:85], v[162:165], v[194:197], v[82:85]
	v_mfma_i32_16x16x64_i8 v[134:137], v[158:161], v[174:177], v[134:137]
	v_mfma_i32_16x16x64_i8 v[130:133], v[166:169], v[174:177], v[130:133]
	v_mfma_i32_16x16x64_i8 v[118:121], v[158:161], v[182:185], v[118:121]
	v_mfma_i32_16x16x64_i8 v[114:117], v[166:169], v[182:185], v[114:117]
	v_mfma_i32_16x16x64_i8 v[102:105], v[158:161], v[190:193], v[102:105]
	v_mfma_i32_16x16x64_i8 v[98:101], v[166:169], v[190:193], v[98:101]
	v_mfma_i32_16x16x64_i8 v[86:89], v[158:161], v[198:201], v[86:89]
	v_mfma_i32_16x16x64_i8 v[82:85], v[166:169], v[198:201], v[82:85]
	s_setprio 0
	s_barrier
	ds_read_b128 v[170:173], v9 offset:16384
	ds_read_b128 v[174:177], v9 offset:17408
	s_mov_b32 m0, s29
	s_nop 0
	buffer_load_dwordx4 v6, s[8:11], s60 offen lds
	ds_read_b128 v[178:181], v9 offset:18432
	ds_read_b128 v[182:185], v9 offset:19456
	s_add_i32 s61, s60, 0x20000
	s_mov_b32 m0, s34
	s_nop 0
	buffer_load_dwordx4 v7, s[8:11], s60 offen lds
	ds_read_b128 v[186:189], v9 offset:20480
	ds_read_b128 v[190:193], v9 offset:21504
	s_nop 0
	s_mov_b32 m0, s35
	s_nop 0
	buffer_load_dwordx4 v6, s[8:11], s61 offen lds
	ds_read_b128 v[194:197], v9 offset:22528
	ds_read_b128 v[198:201], v9 offset:23552
	s_nop 0
	s_mov_b32 m0, s36
	s_nop 0
	buffer_load_dwordx4 v7, s[8:11], s61 offen lds
	s_nop 0
	s_mov_b32 m0, s28
	s_nop 0
	buffer_load_dwordx4 v6, s[12:15], s62 offen lds
	s_nop 0
	s_mov_b32 m0, s38
	s_nop 0
	buffer_load_dwordx4 v7, s[12:15], s62 offen lds
	s_waitcnt vmcnt(8)
	s_waitcnt lgkmcnt(0)
	s_barrier
	s_setprio 1
	s_waitcnt lgkmcnt(7)
	v_mfma_i32_16x16x64_i8 v[78:81], v[10:13], v[170:173], v[78:81]
	v_mfma_i32_16x16x64_i8 v[74:77], v[146:149], v[170:173], v[74:77]
	s_waitcnt lgkmcnt(5)
	v_mfma_i32_16x16x64_i8 v[62:65], v[10:13], v[178:181], v[62:65]
	v_mfma_i32_16x16x64_i8 v[58:61], v[146:149], v[178:181], v[58:61]
	s_waitcnt lgkmcnt(3)
	v_mfma_i32_16x16x64_i8 v[46:49], v[10:13], v[186:189], v[46:49]
	v_mfma_i32_16x16x64_i8 v[42:45], v[146:149], v[186:189], v[42:45]
	s_waitcnt lgkmcnt(1)
	v_mfma_i32_16x16x64_i8 v[10:13], v[10:13], v[194:197], v[30:33]
	v_mfma_i32_16x16x64_i8 v[78:81], v[14:17], v[174:177], v[78:81]
	v_mfma_i32_16x16x64_i8 v[74:77], v[150:153], v[174:177], v[74:77]
	v_mfma_i32_16x16x64_i8 v[62:65], v[14:17], v[182:185], v[62:65]
	v_mfma_i32_16x16x64_i8 v[58:61], v[150:153], v[182:185], v[58:61]
	v_mfma_i32_16x16x64_i8 v[46:49], v[14:17], v[190:193], v[46:49]
	v_mfma_i32_16x16x64_i8 v[42:45], v[150:153], v[190:193], v[42:45]
	s_waitcnt lgkmcnt(0)
	v_mfma_i32_16x16x64_i8 v[10:13], v[14:17], v[198:201], v[10:13]
	v_mfma_i32_16x16x64_i8 v[14:17], v[146:149], v[194:197], v[26:29]
	v_mfma_i32_16x16x64_i8 v[14:17], v[150:153], v[198:201], v[14:17]
	s_setprio 0
	s_setprio 1
	v_mfma_i32_16x16x64_i8 v[26:29], v[154:157], v[170:173], v[70:73]
	v_mfma_i32_16x16x64_i8 v[70:73], v[158:161], v[174:177], v[26:29]
	v_mfma_i32_16x16x64_i8 v[26:29], v[162:165], v[170:173], v[66:69]
	v_mfma_i32_16x16x64_i8 v[66:69], v[166:169], v[174:177], v[26:29]
	v_mfma_i32_16x16x64_i8 v[26:29], v[154:157], v[178:181], v[54:57]
	v_mfma_i32_16x16x64_i8 v[54:57], v[158:161], v[182:185], v[26:29]
	v_mfma_i32_16x16x64_i8 v[26:29], v[162:165], v[178:181], v[50:53]
	v_mfma_i32_16x16x64_i8 v[50:53], v[166:169], v[182:185], v[26:29]
	v_mfma_i32_16x16x64_i8 v[26:29], v[154:157], v[186:189], v[38:41]
	v_mfma_i32_16x16x64_i8 v[38:41], v[158:161], v[190:193], v[26:29]
	v_mfma_i32_16x16x64_i8 v[26:29], v[162:165], v[186:189], v[34:37]
	v_mfma_i32_16x16x64_i8 v[22:25], v[154:157], v[194:197], v[22:25]
	v_mfma_i32_16x16x64_i8 v[18:21], v[162:165], v[194:197], v[18:21]
	v_mfma_i32_16x16x64_i8 v[34:37], v[166:169], v[190:193], v[26:29]
	v_mfma_i32_16x16x64_i8 v[22:25], v[158:161], v[198:201], v[22:25]
	v_mfma_i32_16x16x64_i8 v[18:21], v[166:169], v[198:201], v[18:21]
	s_setprio 0
	s_barrier
	v_add_u32_e32 v150, 0x18000, v8
	v_add_u32_e32 v166, 0x1c000, v8
	ds_read_b128 v[26:29], v150
	ds_read_b128 v[30:33], v150 offset:1024
	ds_read_b128 v[146:149], v150 offset:2048
	ds_read_b128 v[150:153], v150 offset:3072
	ds_read_b128 v[154:157], v166
	ds_read_b128 v[158:161], v166 offset:1024
	ds_read_b128 v[162:165], v166 offset:2048
	ds_read_b128 v[166:169], v166 offset:3072
	s_add_i32 s61, s62, 0x20000
	s_mov_b32 m0, s40
	s_nop 0
	buffer_load_dwordx4 v6, s[12:15], s61 offen lds
	s_nop 0
	s_mov_b32 m0, s41
	s_nop 0
	buffer_load_dwordx4 v7, s[12:15], s61 offen lds
	ds_read_b128 v[170:173], v9 offset:32768
	ds_read_b128 v[174:177], v9 offset:33792
	ds_read_b128 v[178:181], v9 offset:34816
	ds_read_b128 v[182:185], v9 offset:35840
	ds_read_b128 v[186:189], v9 offset:36864
	ds_read_b128 v[190:193], v9 offset:37888
	ds_read_b128 v[194:197], v9 offset:38912
	ds_read_b128 v[198:201], v9 offset:39936
	s_waitcnt vmcnt(8)
	s_waitcnt lgkmcnt(0)
	s_barrier
	s_setprio 1
	s_waitcnt lgkmcnt(7)
	v_mfma_i32_16x16x64_i8 v[142:145], v[26:29], v[170:173], v[142:145]
	v_mfma_i32_16x16x64_i8 v[138:141], v[146:149], v[170:173], v[138:141]
	s_waitcnt lgkmcnt(5)
	v_mfma_i32_16x16x64_i8 v[126:129], v[26:29], v[178:181], v[126:129]
	v_mfma_i32_16x16x64_i8 v[122:125], v[146:149], v[178:181], v[122:125]
	s_waitcnt lgkmcnt(3)
	v_mfma_i32_16x16x64_i8 v[110:113], v[26:29], v[186:189], v[110:113]
	v_mfma_i32_16x16x64_i8 v[106:109], v[146:149], v[186:189], v[106:109]
	s_waitcnt lgkmcnt(1)
	v_mfma_i32_16x16x64_i8 v[94:97], v[26:29], v[194:197], v[94:97]
	v_mfma_i32_16x16x64_i8 v[90:93], v[146:149], v[194:197], v[90:93]
	v_mfma_i32_16x16x64_i8 v[142:145], v[30:33], v[174:177], v[142:145]
	v_mfma_i32_16x16x64_i8 v[138:141], v[150:153], v[174:177], v[138:141]
	v_mfma_i32_16x16x64_i8 v[126:129], v[30:33], v[182:185], v[126:129]
	v_mfma_i32_16x16x64_i8 v[122:125], v[150:153], v[182:185], v[122:125]
	v_mfma_i32_16x16x64_i8 v[110:113], v[30:33], v[190:193], v[110:113]
	v_mfma_i32_16x16x64_i8 v[106:109], v[150:153], v[190:193], v[106:109]
	s_waitcnt lgkmcnt(0)
	v_mfma_i32_16x16x64_i8 v[94:97], v[30:33], v[198:201], v[94:97]
	v_mfma_i32_16x16x64_i8 v[90:93], v[150:153], v[198:201], v[90:93]
	s_setprio 0
	s_setprio 1
	v_mfma_i32_16x16x64_i8 v[134:137], v[154:157], v[170:173], v[134:137]
	v_mfma_i32_16x16x64_i8 v[130:133], v[162:165], v[170:173], v[130:133]
	v_mfma_i32_16x16x64_i8 v[118:121], v[154:157], v[178:181], v[118:121]
	v_mfma_i32_16x16x64_i8 v[114:117], v[162:165], v[178:181], v[114:117]
	v_mfma_i32_16x16x64_i8 v[102:105], v[154:157], v[186:189], v[102:105]
	v_mfma_i32_16x16x64_i8 v[98:101], v[162:165], v[186:189], v[98:101]
	v_mfma_i32_16x16x64_i8 v[86:89], v[154:157], v[194:197], v[86:89]
	v_mfma_i32_16x16x64_i8 v[82:85], v[162:165], v[194:197], v[82:85]
	v_mfma_i32_16x16x64_i8 v[134:137], v[158:161], v[174:177], v[134:137]
	v_mfma_i32_16x16x64_i8 v[130:133], v[166:169], v[174:177], v[130:133]
	v_mfma_i32_16x16x64_i8 v[118:121], v[158:161], v[182:185], v[118:121]
	v_mfma_i32_16x16x64_i8 v[114:117], v[166:169], v[182:185], v[114:117]
	v_mfma_i32_16x16x64_i8 v[102:105], v[158:161], v[190:193], v[102:105]
	v_mfma_i32_16x16x64_i8 v[98:101], v[166:169], v[190:193], v[98:101]
	v_mfma_i32_16x16x64_i8 v[86:89], v[158:161], v[198:201], v[86:89]
	v_mfma_i32_16x16x64_i8 v[82:85], v[166:169], v[198:201], v[82:85]
	s_setprio 0
	s_barrier
	ds_read_b128 v[170:173], v9 offset:49152
	ds_read_b128 v[174:177], v9 offset:50176
	s_or_b32 s61, s60, 0x80
	s_mov_b32 m0, s42
	s_nop 0
	buffer_load_dwordx4 v6, s[8:11], s61 offen lds
	ds_read_b128 v[178:181], v9 offset:51200
	ds_read_b128 v[182:185], v9 offset:52224
	s_add_i32 s60, s60, 0x20080
	s_mov_b32 m0, s43
	s_nop 0
	buffer_load_dwordx4 v7, s[8:11], s61 offen lds
	ds_read_b128 v[186:189], v9 offset:53248
	ds_read_b128 v[190:193], v9 offset:54272
	s_nop 0
	s_mov_b32 m0, s46
	s_nop 0
	buffer_load_dwordx4 v6, s[8:11], s60 offen lds
	ds_read_b128 v[194:197], v9 offset:55296
	ds_read_b128 v[198:201], v9 offset:56320
	s_nop 0
	s_mov_b32 m0, s47
	s_nop 0
	buffer_load_dwordx4 v7, s[8:11], s60 offen lds
	s_nop 0
	s_mov_b32 m0, s44
	s_nop 0
	buffer_load_dwordx4 v6, s[12:15], s59 offen lds
	s_nop 0
	s_mov_b32 m0, s45
	s_nop 0
	buffer_load_dwordx4 v7, s[12:15], s59 offen lds
	s_waitcnt vmcnt(8)
	s_waitcnt lgkmcnt(0)
	s_barrier
	s_setprio 1
	s_waitcnt lgkmcnt(7)
	v_mfma_i32_16x16x64_i8 v[78:81], v[26:29], v[170:173], v[78:81]
	s_waitcnt lgkmcnt(5)
	v_mfma_i32_16x16x64_i8 v[62:65], v[26:29], v[178:181], v[62:65]
	s_waitcnt lgkmcnt(3)
	v_mfma_i32_16x16x64_i8 v[46:49], v[26:29], v[186:189], v[46:49]
	s_waitcnt lgkmcnt(1)
	v_mfma_i32_16x16x64_i8 v[10:13], v[26:29], v[194:197], v[10:13]
	v_mfma_i32_16x16x64_i8 v[78:81], v[30:33], v[174:177], v[78:81]
	v_mfma_i32_16x16x64_i8 v[74:77], v[146:149], v[170:173], v[74:77]
	v_mfma_i32_16x16x64_i8 v[62:65], v[30:33], v[182:185], v[62:65]
	v_mfma_i32_16x16x64_i8 v[58:61], v[146:149], v[178:181], v[58:61]
	v_mfma_i32_16x16x64_i8 v[46:49], v[30:33], v[190:193], v[46:49]
	v_mfma_i32_16x16x64_i8 v[42:45], v[146:149], v[186:189], v[42:45]
	s_waitcnt lgkmcnt(0)
	v_mfma_i32_16x16x64_i8 v[30:33], v[30:33], v[198:201], v[10:13]
	v_mfma_i32_16x16x64_i8 v[10:13], v[146:149], v[194:197], v[14:17]
	v_mfma_i32_16x16x64_i8 v[74:77], v[150:153], v[174:177], v[74:77]
	v_mfma_i32_16x16x64_i8 v[58:61], v[150:153], v[182:185], v[58:61]
	v_mfma_i32_16x16x64_i8 v[42:45], v[150:153], v[190:193], v[42:45]
	v_mfma_i32_16x16x64_i8 v[26:29], v[150:153], v[198:201], v[10:13]
	s_setprio 0
	s_setprio 1
	v_mfma_i32_16x16x64_i8 v[10:13], v[154:157], v[170:173], v[70:73]
	v_mfma_i32_16x16x64_i8 v[70:73], v[158:161], v[174:177], v[10:13]
	v_mfma_i32_16x16x64_i8 v[10:13], v[162:165], v[170:173], v[66:69]
	v_mfma_i32_16x16x64_i8 v[66:69], v[166:169], v[174:177], v[10:13]
	v_mfma_i32_16x16x64_i8 v[10:13], v[154:157], v[178:181], v[54:57]
	v_mfma_i32_16x16x64_i8 v[54:57], v[158:161], v[182:185], v[10:13]
	v_mfma_i32_16x16x64_i8 v[10:13], v[162:165], v[178:181], v[50:53]
	v_mfma_i32_16x16x64_i8 v[50:53], v[166:169], v[182:185], v[10:13]
	v_mfma_i32_16x16x64_i8 v[10:13], v[154:157], v[186:189], v[38:41]
	v_mfma_i32_16x16x64_i8 v[38:41], v[158:161], v[190:193], v[10:13]
	v_mfma_i32_16x16x64_i8 v[10:13], v[162:165], v[186:189], v[34:37]
	v_mfma_i32_16x16x64_i8 v[34:37], v[166:169], v[190:193], v[10:13]
	v_mfma_i32_16x16x64_i8 v[10:13], v[154:157], v[194:197], v[22:25]
	v_mfma_i32_16x16x64_i8 v[22:25], v[158:161], v[198:201], v[10:13]
	v_mfma_i32_16x16x64_i8 v[10:13], v[162:165], v[194:197], v[18:21]
	v_mfma_i32_16x16x64_i8 v[18:21], v[166:169], v[198:201], v[10:13]
	s_setprio 0
	s_barrier
	s_add_i32 s55, s55, 2
	s_addk_i32 s58, 0x100
	s_cmp_lt_u32 s55, 6
	s_cbranch_scc1 .LBB0_943
	s_andn2_b64 vcc, exec, s[6:7]
	s_cbranch_vccz .LBB0_935
	v_cvt_f32_i32_e32 v142, v142
	v_cvt_f32_i32_e32 v143, v143
	v_cvt_f32_i32_e32 v144, v144
	v_cvt_f32_i32_e32 v145, v145
	v_cvt_f32_i32_e32 v138, v138
	v_cvt_f32_i32_e32 v139, v139
	v_cvt_f32_i32_e32 v140, v140
	v_cvt_f32_i32_e32 v141, v141
	v_cvt_f32_i32_e32 v126, v126
	v_cvt_f32_i32_e32 v127, v127
	v_cvt_f32_i32_e32 v128, v128
	v_cvt_f32_i32_e32 v129, v129
	v_cvt_f32_i32_e32 v122, v122
	v_cvt_f32_i32_e32 v123, v123
	v_cvt_f32_i32_e32 v124, v124
	v_cvt_f32_i32_e32 v125, v125
	v_cvt_f32_i32_e32 v110, v110
	v_cvt_f32_i32_e32 v111, v111
	v_cvt_f32_i32_e32 v112, v112
	v_cvt_f32_i32_e32 v113, v113
	v_cvt_f32_i32_e32 v106, v106
	v_cvt_f32_i32_e32 v107, v107
	v_cvt_f32_i32_e32 v108, v108
	v_cvt_f32_i32_e32 v109, v109
	v_cvt_f32_i32_e32 v94, v94
	v_cvt_f32_i32_e32 v95, v95
	v_cvt_f32_i32_e32 v96, v96
	v_cvt_f32_i32_e32 v97, v97
	v_cvt_f32_i32_e32 v90, v90
	v_cvt_f32_i32_e32 v91, v91
	v_cvt_f32_i32_e32 v92, v92
	v_cvt_f32_i32_e32 v93, v93
	v_cvt_f32_i32_e32 v134, v134
	v_cvt_f32_i32_e32 v135, v135
	v_cvt_f32_i32_e32 v136, v136
	v_cvt_f32_i32_e32 v137, v137
	v_cvt_f32_i32_e32 v130, v130
	v_cvt_f32_i32_e32 v131, v131
	v_cvt_f32_i32_e32 v132, v132
	v_cvt_f32_i32_e32 v133, v133
	v_cvt_f32_i32_e32 v118, v118
	v_cvt_f32_i32_e32 v119, v119
	v_cvt_f32_i32_e32 v120, v120
	v_cvt_f32_i32_e32 v121, v121
	v_cvt_f32_i32_e32 v114, v114
	v_cvt_f32_i32_e32 v115, v115
	v_cvt_f32_i32_e32 v116, v116
	v_cvt_f32_i32_e32 v117, v117
	v_cvt_f32_i32_e32 v102, v102
	v_cvt_f32_i32_e32 v103, v103
	v_cvt_f32_i32_e32 v104, v104
	v_cvt_f32_i32_e32 v105, v105
	v_cvt_f32_i32_e32 v98, v98
	v_cvt_f32_i32_e32 v99, v99
	v_cvt_f32_i32_e32 v100, v100
	v_cvt_f32_i32_e32 v101, v101
	v_cvt_f32_i32_e32 v86, v86
	v_cvt_f32_i32_e32 v87, v87
	v_cvt_f32_i32_e32 v88, v88
	v_cvt_f32_i32_e32 v89, v89
	v_cvt_f32_i32_e32 v82, v82
	v_cvt_f32_i32_e32 v83, v83
	v_cvt_f32_i32_e32 v84, v84
	v_cvt_f32_i32_e32 v85, v85
	v_cvt_f32_i32_e32 v78, v78
	v_cvt_f32_i32_e32 v79, v79
	v_cvt_f32_i32_e32 v80, v80
	v_cvt_f32_i32_e32 v81, v81
	v_cvt_f32_i32_e32 v74, v74
	v_cvt_f32_i32_e32 v75, v75
	v_cvt_f32_i32_e32 v76, v76
	v_cvt_f32_i32_e32 v77, v77
	v_cvt_f32_i32_e32 v62, v62
	v_cvt_f32_i32_e32 v63, v63
	v_cvt_f32_i32_e32 v64, v64
	v_cvt_f32_i32_e32 v65, v65
	v_cvt_f32_i32_e32 v58, v58
	v_cvt_f32_i32_e32 v59, v59
	v_cvt_f32_i32_e32 v60, v60
	v_cvt_f32_i32_e32 v61, v61
	v_cvt_f32_i32_e32 v46, v46
	v_cvt_f32_i32_e32 v47, v47
	v_cvt_f32_i32_e32 v48, v48
	v_cvt_f32_i32_e32 v49, v49
	v_cvt_f32_i32_e32 v42, v42
	v_cvt_f32_i32_e32 v43, v43
	v_cvt_f32_i32_e32 v44, v44
	v_cvt_f32_i32_e32 v45, v45
	v_cvt_f32_i32_e32 v30, v30
	v_cvt_f32_i32_e32 v31, v31
	v_cvt_f32_i32_e32 v32, v32
	v_cvt_f32_i32_e32 v33, v33
	v_cvt_f32_i32_e32 v26, v26
	v_cvt_f32_i32_e32 v27, v27
	v_cvt_f32_i32_e32 v28, v28
	v_cvt_f32_i32_e32 v29, v29
	v_cvt_f32_i32_e32 v70, v70
	v_cvt_f32_i32_e32 v71, v71
	v_cvt_f32_i32_e32 v72, v72
	v_cvt_f32_i32_e32 v73, v73
	v_cvt_f32_i32_e32 v66, v66
	v_cvt_f32_i32_e32 v67, v67
	v_cvt_f32_i32_e32 v68, v68
	v_cvt_f32_i32_e32 v69, v69
	v_cvt_f32_i32_e32 v54, v54
	v_cvt_f32_i32_e32 v55, v55
	v_cvt_f32_i32_e32 v56, v56
	v_cvt_f32_i32_e32 v57, v57
	v_cvt_f32_i32_e32 v50, v50
	v_cvt_f32_i32_e32 v51, v51
	v_cvt_f32_i32_e32 v52, v52
	v_cvt_f32_i32_e32 v53, v53
	v_cvt_f32_i32_e32 v38, v38
	v_cvt_f32_i32_e32 v39, v39
	v_cvt_f32_i32_e32 v40, v40
	v_cvt_f32_i32_e32 v41, v41
	v_cvt_f32_i32_e32 v34, v34
	v_cvt_f32_i32_e32 v35, v35
	v_cvt_f32_i32_e32 v36, v36
	v_cvt_f32_i32_e32 v37, v37
	v_cvt_f32_i32_e32 v22, v22
	v_cvt_f32_i32_e32 v23, v23
	v_cvt_f32_i32_e32 v24, v24
	v_cvt_f32_i32_e32 v25, v25
	v_cvt_f32_i32_e32 v18, v18
	v_cvt_f32_i32_e32 v19, v19
	v_cvt_f32_i32_e32 v20, v20
	v_cvt_f32_i32_e32 v21, v21
	s_andn2_b64 vcc, exec, s[4:5]
	s_cbranch_vccnz .LBB0_936

.LBB0_1072:
	ds_read_b128 v[136:139], v152
	ds_read_b128 v[140:143], v152 offset:1024
	ds_read_b128 v[158:161], v152 offset:2048
	ds_read_b128 v[162:165], v152 offset:3072
	ds_read_b128 v[166:169], v153
	ds_read_b128 v[170:173], v153 offset:1024
	ds_read_b128 v[174:177], v153 offset:2048
	ds_read_b128 v[178:181], v153 offset:3072
	s_add_i32 s60, s55, 0xfffe0080
	s_cmp_eq_u32 s59, 4
	s_cselect_b32 s62, s1, s60
	s_cselect_b32 s61, s54, s58
	s_or_b32 s60, s62, 0x80
	s_mov_b32 m0, s42
	s_nop 0
	buffer_load_dwordx4 v146, s[12:15], s55 offen lds
	s_nop 0
	s_mov_b32 m0, s43
	s_nop 0
	buffer_load_dwordx4 v147, s[12:15], s55 offen lds
	ds_read_b128 v[182:185], v154
	ds_read_b128 v[186:189], v154 offset:1024
	ds_read_b128 v[190:193], v154 offset:2048
	ds_read_b128 v[194:197], v154 offset:3072
	ds_read_b128 v[198:201], v154 offset:4096
	ds_read_b128 v[202:205], v154 offset:5120
	ds_read_b128 v[206:209], v154 offset:6144
	ds_read_b128 v[210:213], v154 offset:7168
	s_waitcnt vmcnt(8)
	s_waitcnt lgkmcnt(0)
	s_barrier
	s_setprio 1
	s_waitcnt lgkmcnt(0)
	v_mfma_i32_16x16x64_i8 v[126:129], v[136:139], v[182:185], v[126:129]
	v_mfma_i32_16x16x64_i8 v[122:125], v[158:161], v[182:185], v[122:125]
	v_mfma_i32_16x16x64_i8 v[118:121], v[136:139], v[190:193], v[118:121]
	v_mfma_i32_16x16x64_i8 v[114:117], v[158:161], v[190:193], v[114:117]
	v_mfma_i32_16x16x64_i8 v[110:113], v[136:139], v[198:201], v[110:113]
	v_mfma_i32_16x16x64_i8 v[106:109], v[158:161], v[198:201], v[106:109]
	v_mfma_i32_16x16x64_i8 v[102:105], v[136:139], v[206:209], v[102:105]
	v_mfma_i32_16x16x64_i8 v[98:101], v[158:161], v[206:209], v[98:101]
	v_mfma_i32_16x16x64_i8 v[126:129], v[140:143], v[186:189], v[126:129]
	v_mfma_i32_16x16x64_i8 v[122:125], v[162:165], v[186:189], v[122:125]
	v_mfma_i32_16x16x64_i8 v[118:121], v[140:143], v[194:197], v[118:121]
	v_mfma_i32_16x16x64_i8 v[114:117], v[162:165], v[194:197], v[114:117]
	v_mfma_i32_16x16x64_i8 v[110:113], v[140:143], v[202:205], v[110:113]
	v_mfma_i32_16x16x64_i8 v[106:109], v[162:165], v[202:205], v[106:109]
	v_mfma_i32_16x16x64_i8 v[102:105], v[140:143], v[210:213], v[102:105]
	v_mfma_i32_16x16x64_i8 v[98:101], v[162:165], v[210:213], v[98:101]
	s_setprio 0
	s_setprio 1
	v_mfma_i32_16x16x64_i8 v[94:97], v[166:169], v[182:185], v[94:97]
	v_mfma_i32_16x16x64_i8 v[90:93], v[174:177], v[182:185], v[90:93]
	v_mfma_i32_16x16x64_i8 v[86:89], v[166:169], v[190:193], v[86:89]
	v_mfma_i32_16x16x64_i8 v[82:85], v[174:177], v[190:193], v[82:85]
	v_mfma_i32_16x16x64_i8 v[78:81], v[166:169], v[198:201], v[78:81]
	v_mfma_i32_16x16x64_i8 v[74:77], v[174:177], v[198:201], v[74:77]
	v_mfma_i32_16x16x64_i8 v[70:73], v[166:169], v[206:209], v[70:73]
	v_mfma_i32_16x16x64_i8 v[66:69], v[174:177], v[206:209], v[66:69]
	v_mfma_i32_16x16x64_i8 v[94:97], v[170:173], v[186:189], v[94:97]
	v_mfma_i32_16x16x64_i8 v[90:93], v[178:181], v[186:189], v[90:93]
	v_mfma_i32_16x16x64_i8 v[86:89], v[170:173], v[194:197], v[86:89]
	v_mfma_i32_16x16x64_i8 v[82:85], v[178:181], v[194:197], v[82:85]
	v_mfma_i32_16x16x64_i8 v[78:81], v[170:173], v[202:205], v[78:81]
	v_mfma_i32_16x16x64_i8 v[74:77], v[178:181], v[202:205], v[74:77]
	v_mfma_i32_16x16x64_i8 v[70:73], v[170:173], v[210:213], v[70:73]
	v_mfma_i32_16x16x64_i8 v[66:69], v[178:181], v[210:213], v[66:69]
	s_setprio 0
	s_barrier
	ds_read_b128 v[182:185], v154 offset:16384
	ds_read_b128 v[186:189], v154 offset:17408
	s_mov_b32 m0, s27
	s_nop 0
	buffer_load_dwordx4 v144, s[8:11], s61 offen lds
	ds_read_b128 v[190:193], v154 offset:18432
	ds_read_b128 v[194:197], v154 offset:19456
	s_add_i32 s63, s61, 0x20000
	s_mov_b32 m0, s28
	s_nop 0
	buffer_load_dwordx4 v145, s[8:11], s61 offen lds
	ds_read_b128 v[198:201], v154 offset:20480
	ds_read_b128 v[202:205], v154 offset:21504
	s_nop 0
	s_mov_b32 m0, s29
	s_nop 0
	buffer_load_dwordx4 v144, s[8:11], s63 offen lds
	ds_read_b128 v[206:209], v154 offset:22528
	ds_read_b128 v[210:213], v154 offset:23552
	s_nop 0
	s_mov_b32 m0, s30
	s_nop 0
	buffer_load_dwordx4 v145, s[8:11], s63 offen lds
	s_nop 0
	s_mov_b32 m0, s26
	s_nop 0
	buffer_load_dwordx4 v146, s[12:15], s62 offen lds
	s_nop 0
	s_mov_b32 m0, s2
	s_nop 0
	buffer_load_dwordx4 v147, s[12:15], s62 offen lds
	s_waitcnt vmcnt(8)
	s_waitcnt lgkmcnt(0)
	s_barrier
	s_setprio 1
	s_waitcnt lgkmcnt(0)
	v_mfma_i32_16x16x64_i8 v[62:65], v[136:139], v[182:185], v[62:65]
	v_mfma_i32_16x16x64_i8 v[58:61], v[158:161], v[182:185], v[58:61]
	v_mfma_i32_16x16x64_i8 v[54:57], v[136:139], v[190:193], v[54:57]
	v_mfma_i32_16x16x64_i8 v[50:53], v[158:161], v[190:193], v[50:53]
	v_mfma_i32_16x16x64_i8 v[46:49], v[136:139], v[198:201], v[46:49]
	v_mfma_i32_16x16x64_i8 v[42:45], v[158:161], v[198:201], v[42:45]
	v_mfma_i32_16x16x64_i8 v[38:41], v[136:139], v[206:209], v[38:41]
	v_mfma_i32_16x16x64_i8 v[34:37], v[158:161], v[206:209], v[34:37]
	v_mfma_i32_16x16x64_i8 v[62:65], v[140:143], v[186:189], v[62:65]
	v_mfma_i32_16x16x64_i8 v[58:61], v[162:165], v[186:189], v[58:61]
	v_mfma_i32_16x16x64_i8 v[54:57], v[140:143], v[194:197], v[54:57]
	v_mfma_i32_16x16x64_i8 v[50:53], v[162:165], v[194:197], v[50:53]
	v_mfma_i32_16x16x64_i8 v[46:49], v[140:143], v[202:205], v[46:49]
	v_mfma_i32_16x16x64_i8 v[42:45], v[162:165], v[202:205], v[42:45]
	v_mfma_i32_16x16x64_i8 v[38:41], v[140:143], v[210:213], v[38:41]
	v_mfma_i32_16x16x64_i8 v[34:37], v[162:165], v[210:213], v[34:37]
	s_setprio 0
	s_setprio 1
	v_mfma_i32_16x16x64_i8 v[30:33], v[166:169], v[182:185], v[30:33]
	v_mfma_i32_16x16x64_i8 v[26:29], v[174:177], v[182:185], v[26:29]
	v_mfma_i32_16x16x64_i8 v[22:25], v[166:169], v[190:193], v[22:25]
	v_mfma_i32_16x16x64_i8 v[18:21], v[174:177], v[190:193], v[18:21]
	v_mfma_i32_16x16x64_i8 v[14:17], v[166:169], v[198:201], v[14:17]
	v_mfma_i32_16x16x64_i8 v[10:13], v[174:177], v[198:201], v[10:13]
	v_mfma_i32_16x16x64_i8 v[6:9], v[166:169], v[206:209], v[6:9]
	v_mfma_i32_16x16x64_i8 v[2:5], v[174:177], v[206:209], v[2:5]
	v_mfma_i32_16x16x64_i8 v[30:33], v[170:173], v[186:189], v[30:33]
	v_mfma_i32_16x16x64_i8 v[26:29], v[178:181], v[186:189], v[26:29]
	v_mfma_i32_16x16x64_i8 v[22:25], v[170:173], v[194:197], v[22:25]
	v_mfma_i32_16x16x64_i8 v[18:21], v[178:181], v[194:197], v[18:21]
	v_mfma_i32_16x16x64_i8 v[14:17], v[170:173], v[202:205], v[14:17]
	v_mfma_i32_16x16x64_i8 v[10:13], v[178:181], v[202:205], v[10:13]
	v_mfma_i32_16x16x64_i8 v[6:9], v[170:173], v[210:213], v[6:9]
	v_mfma_i32_16x16x64_i8 v[2:5], v[178:181], v[210:213], v[2:5]
	s_setprio 0
	s_barrier
	ds_read_b128 v[136:139], v155
	ds_read_b128 v[140:143], v155 offset:1024
	ds_read_b128 v[158:161], v155 offset:2048
	ds_read_b128 v[162:165], v155 offset:3072
	ds_read_b128 v[166:169], v156
	ds_read_b128 v[170:173], v156 offset:1024
	ds_read_b128 v[174:177], v156 offset:2048
	ds_read_b128 v[178:181], v156 offset:3072
	s_add_i32 s62, s62, 0x20000
	s_mov_b32 m0, s3
	s_nop 0
	buffer_load_dwordx4 v146, s[12:15], s62 offen lds
	s_nop 0
	s_mov_b32 m0, s31
	s_nop 0
	buffer_load_dwordx4 v147, s[12:15], s62 offen lds
	ds_read_b128 v[182:185], v154 offset:32768
	ds_read_b128 v[186:189], v154 offset:33792
	ds_read_b128 v[190:193], v154 offset:34816
	ds_read_b128 v[194:197], v154 offset:35840
	ds_read_b128 v[198:201], v154 offset:36864
	ds_read_b128 v[202:205], v154 offset:37888
	ds_read_b128 v[206:209], v154 offset:38912
	ds_read_b128 v[210:213], v154 offset:39936
	s_waitcnt vmcnt(8)
	s_waitcnt lgkmcnt(0)
	s_barrier
	s_setprio 1
	s_waitcnt lgkmcnt(0)
	v_mfma_i32_16x16x64_i8 v[126:129], v[136:139], v[182:185], v[126:129]
	v_mfma_i32_16x16x64_i8 v[122:125], v[158:161], v[182:185], v[122:125]
	v_mfma_i32_16x16x64_i8 v[118:121], v[136:139], v[190:193], v[118:121]
	v_mfma_i32_16x16x64_i8 v[114:117], v[158:161], v[190:193], v[114:117]
	v_mfma_i32_16x16x64_i8 v[110:113], v[136:139], v[198:201], v[110:113]
	v_mfma_i32_16x16x64_i8 v[106:109], v[158:161], v[198:201], v[106:109]
	v_mfma_i32_16x16x64_i8 v[102:105], v[136:139], v[206:209], v[102:105]
	v_mfma_i32_16x16x64_i8 v[98:101], v[158:161], v[206:209], v[98:101]
	v_mfma_i32_16x16x64_i8 v[126:129], v[140:143], v[186:189], v[126:129]
	v_mfma_i32_16x16x64_i8 v[122:125], v[162:165], v[186:189], v[122:125]
	v_mfma_i32_16x16x64_i8 v[118:121], v[140:143], v[194:197], v[118:121]
	v_mfma_i32_16x16x64_i8 v[114:117], v[162:165], v[194:197], v[114:117]
	v_mfma_i32_16x16x64_i8 v[110:113], v[140:143], v[202:205], v[110:113]
	v_mfma_i32_16x16x64_i8 v[106:109], v[162:165], v[202:205], v[106:109]
	v_mfma_i32_16x16x64_i8 v[102:105], v[140:143], v[210:213], v[102:105]
	v_mfma_i32_16x16x64_i8 v[98:101], v[162:165], v[210:213], v[98:101]
	s_setprio 0
	s_setprio 1
	v_mfma_i32_16x16x64_i8 v[94:97], v[166:169], v[182:185], v[94:97]
	v_mfma_i32_16x16x64_i8 v[90:93], v[174:177], v[182:185], v[90:93]
	v_mfma_i32_16x16x64_i8 v[86:89], v[166:169], v[190:193], v[86:89]
	v_mfma_i32_16x16x64_i8 v[82:85], v[174:177], v[190:193], v[82:85]
	v_mfma_i32_16x16x64_i8 v[78:81], v[166:169], v[198:201], v[78:81]
	v_mfma_i32_16x16x64_i8 v[74:77], v[174:177], v[198:201], v[74:77]
	v_mfma_i32_16x16x64_i8 v[70:73], v[166:169], v[206:209], v[70:73]
	v_mfma_i32_16x16x64_i8 v[66:69], v[174:177], v[206:209], v[66:69]
	v_mfma_i32_16x16x64_i8 v[94:97], v[170:173], v[186:189], v[94:97]
	v_mfma_i32_16x16x64_i8 v[90:93], v[178:181], v[186:189], v[90:93]
	v_mfma_i32_16x16x64_i8 v[86:89], v[170:173], v[194:197], v[86:89]
	v_mfma_i32_16x16x64_i8 v[82:85], v[178:181], v[194:197], v[82:85]
	v_mfma_i32_16x16x64_i8 v[78:81], v[170:173], v[202:205], v[78:81]
	v_mfma_i32_16x16x64_i8 v[74:77], v[178:181], v[202:205], v[74:77]
	v_mfma_i32_16x16x64_i8 v[70:73], v[170:173], v[210:213], v[70:73]
	v_mfma_i32_16x16x64_i8 v[66:69], v[178:181], v[210:213], v[66:69]
	s_setprio 0
	s_barrier
	ds_read_b128 v[182:185], v154 offset:49152
	ds_read_b128 v[186:189], v154 offset:50176
	s_or_b32 s62, s61, 0x80
	s_mov_b32 m0, s35
	s_nop 0
	buffer_load_dwordx4 v144, s[8:11], s62 offen lds
	ds_read_b128 v[190:193], v154 offset:51200
	ds_read_b128 v[194:197], v154 offset:52224
	s_add_i32 s61, s61, 0x20080
	s_mov_b32 m0, s36
	s_nop 0
	buffer_load_dwordx4 v145, s[8:11], s62 offen lds
	ds_read_b128 v[198:201], v154 offset:53248
	ds_read_b128 v[202:205], v154 offset:54272
	s_nop 0
	s_mov_b32 m0, s39
	s_nop 0
	buffer_load_dwordx4 v144, s[8:11], s61 offen lds
	ds_read_b128 v[206:209], v154 offset:55296
	ds_read_b128 v[210:213], v154 offset:56320
	s_nop 0
	s_mov_b32 m0, s40
	s_nop 0
	buffer_load_dwordx4 v145, s[8:11], s61 offen lds
	s_nop 0
	s_mov_b32 m0, s37
	s_nop 0
	buffer_load_dwordx4 v146, s[12:15], s60 offen lds
	s_nop 0
	s_mov_b32 m0, s38
	s_nop 0
	buffer_load_dwordx4 v147, s[12:15], s60 offen lds
	s_waitcnt vmcnt(8)
	s_waitcnt lgkmcnt(0)
	s_barrier
	s_setprio 1
	s_waitcnt lgkmcnt(0)
	v_mfma_i32_16x16x64_i8 v[62:65], v[136:139], v[182:185], v[62:65]
	v_mfma_i32_16x16x64_i8 v[58:61], v[158:161], v[182:185], v[58:61]
	v_mfma_i32_16x16x64_i8 v[54:57], v[136:139], v[190:193], v[54:57]
	v_mfma_i32_16x16x64_i8 v[50:53], v[158:161], v[190:193], v[50:53]
	v_mfma_i32_16x16x64_i8 v[46:49], v[136:139], v[198:201], v[46:49]
	v_mfma_i32_16x16x64_i8 v[42:45], v[158:161], v[198:201], v[42:45]
	v_mfma_i32_16x16x64_i8 v[38:41], v[136:139], v[206:209], v[38:41]
	v_mfma_i32_16x16x64_i8 v[34:37], v[158:161], v[206:209], v[34:37]
	v_mfma_i32_16x16x64_i8 v[62:65], v[140:143], v[186:189], v[62:65]
	v_mfma_i32_16x16x64_i8 v[58:61], v[162:165], v[186:189], v[58:61]
	v_mfma_i32_16x16x64_i8 v[54:57], v[140:143], v[194:197], v[54:57]
	v_mfma_i32_16x16x64_i8 v[50:53], v[162:165], v[194:197], v[50:53]
	v_mfma_i32_16x16x64_i8 v[46:49], v[140:143], v[202:205], v[46:49]
	v_mfma_i32_16x16x64_i8 v[42:45], v[162:165], v[202:205], v[42:45]
	v_mfma_i32_16x16x64_i8 v[38:41], v[140:143], v[210:213], v[38:41]
	v_mfma_i32_16x16x64_i8 v[34:37], v[162:165], v[210:213], v[34:37]
	s_setprio 0
	s_setprio 1
	v_mfma_i32_16x16x64_i8 v[30:33], v[166:169], v[182:185], v[30:33]
	v_mfma_i32_16x16x64_i8 v[26:29], v[174:177], v[182:185], v[26:29]
	v_mfma_i32_16x16x64_i8 v[22:25], v[166:169], v[190:193], v[22:25]
	v_mfma_i32_16x16x64_i8 v[18:21], v[174:177], v[190:193], v[18:21]
	v_mfma_i32_16x16x64_i8 v[14:17], v[166:169], v[198:201], v[14:17]
	v_mfma_i32_16x16x64_i8 v[10:13], v[174:177], v[198:201], v[10:13]
	v_mfma_i32_16x16x64_i8 v[6:9], v[166:169], v[206:209], v[6:9]
	v_mfma_i32_16x16x64_i8 v[2:5], v[174:177], v[206:209], v[2:5]
	v_mfma_i32_16x16x64_i8 v[30:33], v[170:173], v[186:189], v[30:33]
	v_mfma_i32_16x16x64_i8 v[26:29], v[178:181], v[186:189], v[26:29]
	v_mfma_i32_16x16x64_i8 v[22:25], v[170:173], v[194:197], v[22:25]
	v_mfma_i32_16x16x64_i8 v[18:21], v[178:181], v[194:197], v[18:21]
	v_mfma_i32_16x16x64_i8 v[14:17], v[170:173], v[202:205], v[14:17]
	v_mfma_i32_16x16x64_i8 v[10:13], v[178:181], v[202:205], v[10:13]
	v_mfma_i32_16x16x64_i8 v[6:9], v[170:173], v[210:213], v[6:9]
	v_mfma_i32_16x16x64_i8 v[2:5], v[178:181], v[210:213], v[2:5]
	s_setprio 0
	s_barrier
	s_add_i32 s59, s59, 2
	s_addk_i32 s55, 0x100
	s_addk_i32 s58, 0x100
	s_cmp_gt_u32 s59, 5
	s_cbranch_scc0 .LBB0_1072
	s_and_b64 vcc, exec, s[20:21]
	s_cbranch_vccz .LBB0_1075
	s_barrier

.LBB0_1135:
	v_add_u32_e32 v150, 0x10000, v136
	v_add_u32_e32 v166, 0x14000, v136
	ds_read_b128 v[138:141], v150
	ds_read_b128 v[142:145], v150 offset:1024
	ds_read_b128 v[146:149], v150 offset:2048
	ds_read_b128 v[150:153], v150 offset:3072
	ds_read_b128 v[154:157], v166
	ds_read_b128 v[158:161], v166 offset:1024
	ds_read_b128 v[162:165], v166 offset:2048
	ds_read_b128 v[166:169], v166 offset:3072
	s_add_i32 s57, s36, s3
	s_add_i32 s56, s30, s3
	s_add_i32 s55, s57, 0x1600
	s_addk_i32 s56, 0x1600
	s_cmp_eq_u32 s3, 0
	s_cselect_b32 s58, s53, s55
	s_cselect_b32 s56, s54, s56
	s_add_i32 s55, s58, 0x80
	s_add_i32 s57, s57, 0xb1580
	s_mov_b32 m0, s46
	s_nop 0
	buffer_load_dwordx4 v134, s[16:19], s57 offen lds
	s_nop 0
	s_mov_b32 m0, s47
	s_nop 0
	buffer_load_dwordx4 v135, s[16:19], s57 offen lds
	ds_read_b128 v[170:173], v137
	ds_read_b128 v[174:177], v137 offset:1024
	ds_read_b128 v[178:181], v137 offset:2048
	ds_read_b128 v[182:185], v137 offset:3072
	ds_read_b128 v[186:189], v137 offset:4096
	ds_read_b128 v[190:193], v137 offset:5120
	ds_read_b128 v[194:197], v137 offset:6144
	ds_read_b128 v[198:201], v137 offset:7168
	s_waitcnt vmcnt(8)
	s_waitcnt lgkmcnt(0)
	s_barrier
	s_setprio 1
	s_waitcnt lgkmcnt(7)
	v_mfma_f32_16x16x32_bf16 v[126:129], v[138:141], v[170:173], v[126:129]
	v_mfma_f32_16x16x32_bf16 v[122:125], v[146:149], v[170:173], v[122:125]
	s_waitcnt lgkmcnt(5)
	v_mfma_f32_16x16x32_bf16 v[118:121], v[138:141], v[178:181], v[118:121]
	v_mfma_f32_16x16x32_bf16 v[106:109], v[146:149], v[178:181], v[106:109]
	s_waitcnt lgkmcnt(3)
	v_mfma_f32_16x16x32_bf16 v[102:105], v[138:141], v[186:189], v[102:105]
	v_mfma_f32_16x16x32_bf16 v[90:93], v[146:149], v[186:189], v[90:93]
	s_waitcnt lgkmcnt(1)
	v_mfma_f32_16x16x32_bf16 v[86:89], v[138:141], v[194:197], v[86:89]
	v_mfma_f32_16x16x32_bf16 v[74:77], v[146:149], v[194:197], v[74:77]
	v_mfma_f32_16x16x32_bf16 v[126:129], v[142:145], v[174:177], v[126:129]
	v_mfma_f32_16x16x32_bf16 v[122:125], v[150:153], v[174:177], v[122:125]
	v_mfma_f32_16x16x32_bf16 v[118:121], v[142:145], v[182:185], v[118:121]
	v_mfma_f32_16x16x32_bf16 v[106:109], v[150:153], v[182:185], v[106:109]
	v_mfma_f32_16x16x32_bf16 v[102:105], v[142:145], v[190:193], v[102:105]
	v_mfma_f32_16x16x32_bf16 v[90:93], v[150:153], v[190:193], v[90:93]
	s_waitcnt lgkmcnt(0)
	v_mfma_f32_16x16x32_bf16 v[86:89], v[142:145], v[198:201], v[86:89]
	v_mfma_f32_16x16x32_bf16 v[74:77], v[150:153], v[198:201], v[74:77]
	s_setprio 0
	s_setprio 1
	v_mfma_f32_16x16x32_bf16 v[114:117], v[154:157], v[170:173], v[114:117]
	v_mfma_f32_16x16x32_bf16 v[110:113], v[162:165], v[170:173], v[110:113]
	v_mfma_f32_16x16x32_bf16 v[98:101], v[154:157], v[178:181], v[98:101]
	v_mfma_f32_16x16x32_bf16 v[94:97], v[162:165], v[178:181], v[94:97]
	v_mfma_f32_16x16x32_bf16 v[82:85], v[154:157], v[186:189], v[82:85]
	v_mfma_f32_16x16x32_bf16 v[78:81], v[162:165], v[186:189], v[78:81]
	v_mfma_f32_16x16x32_bf16 v[70:73], v[154:157], v[194:197], v[70:73]
	v_mfma_f32_16x16x32_bf16 v[66:69], v[162:165], v[194:197], v[66:69]
	v_mfma_f32_16x16x32_bf16 v[114:117], v[158:161], v[174:177], v[114:117]
	v_mfma_f32_16x16x32_bf16 v[110:113], v[166:169], v[174:177], v[110:113]
	v_mfma_f32_16x16x32_bf16 v[98:101], v[158:161], v[182:185], v[98:101]
	v_mfma_f32_16x16x32_bf16 v[94:97], v[166:169], v[182:185], v[94:97]
	v_mfma_f32_16x16x32_bf16 v[82:85], v[158:161], v[190:193], v[82:85]
	v_mfma_f32_16x16x32_bf16 v[78:81], v[166:169], v[190:193], v[78:81]
	v_mfma_f32_16x16x32_bf16 v[70:73], v[158:161], v[198:201], v[70:73]
	v_mfma_f32_16x16x32_bf16 v[66:69], v[166:169], v[198:201], v[66:69]
	s_setprio 0
	s_barrier
	ds_read_b128 v[170:173], v137 offset:16384
	ds_read_b128 v[174:177], v137 offset:17408
	s_mov_b32 m0, s29
	s_nop 0
	buffer_load_dwordx4 v134, s[12:15], s56 offen lds
	ds_read_b128 v[178:181], v137 offset:18432
	ds_read_b128 v[182:185], v137 offset:19456
	s_add_i32 s57, s56, 0xb0000
	s_mov_b32 m0, s33
	s_nop 0
	buffer_load_dwordx4 v135, s[12:15], s56 offen lds
	ds_read_b128 v[186:189], v137 offset:20480
	ds_read_b128 v[190:193], v137 offset:21504
	s_nop 0
	s_mov_b32 m0, s34
	s_nop 0
	buffer_load_dwordx4 v134, s[12:15], s57 offen lds
	ds_read_b128 v[194:197], v137 offset:22528
	ds_read_b128 v[198:201], v137 offset:23552
	s_nop 0
	s_mov_b32 m0, s35
	s_nop 0
	buffer_load_dwordx4 v135, s[12:15], s57 offen lds
	s_nop 0
	s_mov_b32 m0, s28
	s_nop 0
	buffer_load_dwordx4 v134, s[16:19], s58 offen lds
	s_nop 0
	s_mov_b32 m0, s37
	s_nop 0
	buffer_load_dwordx4 v135, s[16:19], s58 offen lds
	s_waitcnt vmcnt(8)
	s_waitcnt lgkmcnt(0)
	s_barrier
	s_setprio 1
	s_waitcnt lgkmcnt(7)
	v_mfma_f32_16x16x32_bf16 v[62:65], v[138:141], v[170:173], v[62:65]
	v_mfma_f32_16x16x32_bf16 v[58:61], v[146:149], v[170:173], v[58:61]
	s_waitcnt lgkmcnt(5)
	v_mfma_f32_16x16x32_bf16 v[54:57], v[138:141], v[178:181], v[54:57]
	v_mfma_f32_16x16x32_bf16 v[42:45], v[146:149], v[178:181], v[42:45]
	s_waitcnt lgkmcnt(3)
	v_mfma_f32_16x16x32_bf16 v[38:41], v[138:141], v[186:189], v[38:41]
	v_mfma_f32_16x16x32_bf16 v[26:29], v[146:149], v[186:189], v[26:29]
	s_waitcnt lgkmcnt(1)
	v_mfma_f32_16x16x32_bf16 v[18:21], v[138:141], v[194:197], v[18:21]
	v_mfma_f32_16x16x32_bf16 v[10:13], v[146:149], v[194:197], v[10:13]
	v_mfma_f32_16x16x32_bf16 v[62:65], v[142:145], v[174:177], v[62:65]
	v_mfma_f32_16x16x32_bf16 v[58:61], v[150:153], v[174:177], v[58:61]
	v_mfma_f32_16x16x32_bf16 v[54:57], v[142:145], v[182:185], v[54:57]
	v_mfma_f32_16x16x32_bf16 v[42:45], v[150:153], v[182:185], v[42:45]
	v_mfma_f32_16x16x32_bf16 v[38:41], v[142:145], v[190:193], v[38:41]
	v_mfma_f32_16x16x32_bf16 v[26:29], v[150:153], v[190:193], v[26:29]
	s_waitcnt lgkmcnt(0)
	v_mfma_f32_16x16x32_bf16 v[18:21], v[142:145], v[198:201], v[18:21]
	v_mfma_f32_16x16x32_bf16 v[10:13], v[150:153], v[198:201], v[10:13]
	s_setprio 0
	s_setprio 1
	v_mfma_f32_16x16x32_bf16 v[50:53], v[154:157], v[170:173], v[50:53]
	v_mfma_f32_16x16x32_bf16 v[46:49], v[162:165], v[170:173], v[46:49]
	v_mfma_f32_16x16x32_bf16 v[34:37], v[154:157], v[178:181], v[34:37]
	v_mfma_f32_16x16x32_bf16 v[30:33], v[162:165], v[178:181], v[30:33]
	v_mfma_f32_16x16x32_bf16 v[22:25], v[154:157], v[186:189], v[22:25]
	v_mfma_f32_16x16x32_bf16 v[14:17], v[162:165], v[186:189], v[14:17]
	v_mfma_f32_16x16x32_bf16 v[6:9], v[154:157], v[194:197], v[6:9]
	v_mfma_f32_16x16x32_bf16 v[2:5], v[162:165], v[194:197], v[2:5]
	v_mfma_f32_16x16x32_bf16 v[50:53], v[158:161], v[174:177], v[50:53]
	v_mfma_f32_16x16x32_bf16 v[46:49], v[166:169], v[174:177], v[46:49]
	v_mfma_f32_16x16x32_bf16 v[34:37], v[158:161], v[182:185], v[34:37]
	v_mfma_f32_16x16x32_bf16 v[30:33], v[166:169], v[182:185], v[30:33]
	v_mfma_f32_16x16x32_bf16 v[22:25], v[158:161], v[190:193], v[22:25]
	v_mfma_f32_16x16x32_bf16 v[14:17], v[166:169], v[190:193], v[14:17]
	v_mfma_f32_16x16x32_bf16 v[6:9], v[158:161], v[198:201], v[6:9]
	v_mfma_f32_16x16x32_bf16 v[2:5], v[166:169], v[198:201], v[2:5]
	s_setprio 0
	s_barrier
	v_add_u32_e32 v150, 0x18000, v136
	v_add_u32_e32 v166, 0x1c000, v136
	ds_read_b128 v[138:141], v150
	ds_read_b128 v[142:145], v150 offset:1024
	ds_read_b128 v[146:149], v150 offset:2048
	ds_read_b128 v[150:153], v150 offset:3072
	ds_read_b128 v[154:157], v166
	ds_read_b128 v[158:161], v166 offset:1024
	ds_read_b128 v[162:165], v166 offset:2048
	ds_read_b128 v[166:169], v166 offset:3072
	s_add_i32 s57, s58, 0xb0000
	s_mov_b32 m0, s38
	s_nop 0
	buffer_load_dwordx4 v134, s[16:19], s57 offen lds
	s_nop 0
	s_mov_b32 m0, s39
	s_nop 0
	buffer_load_dwordx4 v135, s[16:19], s57 offen lds
	ds_read_b128 v[170:173], v137 offset:32768
	ds_read_b128 v[174:177], v137 offset:33792
	ds_read_b128 v[178:181], v137 offset:34816
	ds_read_b128 v[182:185], v137 offset:35840
	ds_read_b128 v[186:189], v137 offset:36864
	ds_read_b128 v[190:193], v137 offset:37888
	ds_read_b128 v[194:197], v137 offset:38912
	ds_read_b128 v[198:201], v137 offset:39936
	s_waitcnt vmcnt(8)
	s_waitcnt lgkmcnt(0)
	s_barrier
	s_setprio 1
	s_waitcnt lgkmcnt(7)
	v_mfma_f32_16x16x32_bf16 v[126:129], v[138:141], v[170:173], v[126:129]
	v_mfma_f32_16x16x32_bf16 v[122:125], v[146:149], v[170:173], v[122:125]
	s_waitcnt lgkmcnt(5)
	v_mfma_f32_16x16x32_bf16 v[118:121], v[138:141], v[178:181], v[118:121]
	v_mfma_f32_16x16x32_bf16 v[106:109], v[146:149], v[178:181], v[106:109]
	s_waitcnt lgkmcnt(3)
	v_mfma_f32_16x16x32_bf16 v[102:105], v[138:141], v[186:189], v[102:105]
	v_mfma_f32_16x16x32_bf16 v[90:93], v[146:149], v[186:189], v[90:93]
	s_waitcnt lgkmcnt(1)
	v_mfma_f32_16x16x32_bf16 v[86:89], v[138:141], v[194:197], v[86:89]
	v_mfma_f32_16x16x32_bf16 v[74:77], v[146:149], v[194:197], v[74:77]
	v_mfma_f32_16x16x32_bf16 v[126:129], v[142:145], v[174:177], v[126:129]
	v_mfma_f32_16x16x32_bf16 v[122:125], v[150:153], v[174:177], v[122:125]
	v_mfma_f32_16x16x32_bf16 v[118:121], v[142:145], v[182:185], v[118:121]
	v_mfma_f32_16x16x32_bf16 v[106:109], v[150:153], v[182:185], v[106:109]
	v_mfma_f32_16x16x32_bf16 v[102:105], v[142:145], v[190:193], v[102:105]
	v_mfma_f32_16x16x32_bf16 v[90:93], v[150:153], v[190:193], v[90:93]
	s_waitcnt lgkmcnt(0)
	v_mfma_f32_16x16x32_bf16 v[86:89], v[142:145], v[198:201], v[86:89]
	v_mfma_f32_16x16x32_bf16 v[74:77], v[150:153], v[198:201], v[74:77]
	s_setprio 0
	s_setprio 1
	v_mfma_f32_16x16x32_bf16 v[114:117], v[154:157], v[170:173], v[114:117]
	v_mfma_f32_16x16x32_bf16 v[110:113], v[162:165], v[170:173], v[110:113]
	v_mfma_f32_16x16x32_bf16 v[98:101], v[154:157], v[178:181], v[98:101]
	v_mfma_f32_16x16x32_bf16 v[94:97], v[162:165], v[178:181], v[94:97]
	v_mfma_f32_16x16x32_bf16 v[82:85], v[154:157], v[186:189], v[82:85]
	v_mfma_f32_16x16x32_bf16 v[78:81], v[162:165], v[186:189], v[78:81]
	v_mfma_f32_16x16x32_bf16 v[70:73], v[154:157], v[194:197], v[70:73]
	v_mfma_f32_16x16x32_bf16 v[66:69], v[162:165], v[194:197], v[66:69]
	v_mfma_f32_16x16x32_bf16 v[114:117], v[158:161], v[174:177], v[114:117]
	v_mfma_f32_16x16x32_bf16 v[110:113], v[166:169], v[174:177], v[110:113]
	v_mfma_f32_16x16x32_bf16 v[98:101], v[158:161], v[182:185], v[98:101]
	v_mfma_f32_16x16x32_bf16 v[94:97], v[166:169], v[182:185], v[94:97]
	v_mfma_f32_16x16x32_bf16 v[82:85], v[158:161], v[190:193], v[82:85]
	v_mfma_f32_16x16x32_bf16 v[78:81], v[166:169], v[190:193], v[78:81]
	v_mfma_f32_16x16x32_bf16 v[70:73], v[158:161], v[198:201], v[70:73]
	v_mfma_f32_16x16x32_bf16 v[66:69], v[166:169], v[198:201], v[66:69]
	s_setprio 0
	s_barrier
	ds_read_b128 v[170:173], v137 offset:49152
	ds_read_b128 v[174:177], v137 offset:50176
	s_add_i32 s57, s56, 0x80
	s_mov_b32 m0, s40
	s_nop 0
	buffer_load_dwordx4 v134, s[12:15], s57 offen lds
	ds_read_b128 v[178:181], v137 offset:51200
	ds_read_b128 v[182:185], v137 offset:52224
	s_add_i32 s56, s56, 0xb0080
	s_mov_b32 m0, s41
	s_nop 0
	buffer_load_dwordx4 v135, s[12:15], s57 offen lds
	ds_read_b128 v[186:189], v137 offset:53248
	ds_read_b128 v[190:193], v137 offset:54272
	s_nop 0
	s_mov_b32 m0, s44
	s_nop 0
	buffer_load_dwordx4 v134, s[12:15], s56 offen lds
	ds_read_b128 v[194:197], v137 offset:55296
	ds_read_b128 v[198:201], v137 offset:56320
	s_nop 0
	s_mov_b32 m0, s45
	s_nop 0
	buffer_load_dwordx4 v135, s[12:15], s56 offen lds
	s_nop 0
	s_mov_b32 m0, s42
	s_nop 0
	buffer_load_dwordx4 v134, s[16:19], s55 offen lds
	s_nop 0
	s_mov_b32 m0, s43
	s_nop 0
	buffer_load_dwordx4 v135, s[16:19], s55 offen lds
	s_waitcnt vmcnt(8)
	s_waitcnt lgkmcnt(0)
	s_barrier
	s_setprio 1
	s_waitcnt lgkmcnt(7)
	v_mfma_f32_16x16x32_bf16 v[62:65], v[138:141], v[170:173], v[62:65]
	v_mfma_f32_16x16x32_bf16 v[58:61], v[146:149], v[170:173], v[58:61]
	s_waitcnt lgkmcnt(5)
	v_mfma_f32_16x16x32_bf16 v[54:57], v[138:141], v[178:181], v[54:57]
	v_mfma_f32_16x16x32_bf16 v[42:45], v[146:149], v[178:181], v[42:45]
	s_waitcnt lgkmcnt(3)
	v_mfma_f32_16x16x32_bf16 v[38:41], v[138:141], v[186:189], v[38:41]
	v_mfma_f32_16x16x32_bf16 v[26:29], v[146:149], v[186:189], v[26:29]
	s_waitcnt lgkmcnt(1)
	v_mfma_f32_16x16x32_bf16 v[18:21], v[138:141], v[194:197], v[18:21]
	v_mfma_f32_16x16x32_bf16 v[10:13], v[146:149], v[194:197], v[10:13]
	v_mfma_f32_16x16x32_bf16 v[62:65], v[142:145], v[174:177], v[62:65]
	v_mfma_f32_16x16x32_bf16 v[58:61], v[150:153], v[174:177], v[58:61]
	v_mfma_f32_16x16x32_bf16 v[54:57], v[142:145], v[182:185], v[54:57]
	v_mfma_f32_16x16x32_bf16 v[42:45], v[150:153], v[182:185], v[42:45]
	v_mfma_f32_16x16x32_bf16 v[38:41], v[142:145], v[190:193], v[38:41]
	v_mfma_f32_16x16x32_bf16 v[26:29], v[150:153], v[190:193], v[26:29]
	s_waitcnt lgkmcnt(0)
	v_mfma_f32_16x16x32_bf16 v[18:21], v[142:145], v[198:201], v[18:21]
	v_mfma_f32_16x16x32_bf16 v[10:13], v[150:153], v[198:201], v[10:13]
	s_setprio 0
	s_setprio 1
	v_mfma_f32_16x16x32_bf16 v[50:53], v[154:157], v[170:173], v[50:53]
	v_mfma_f32_16x16x32_bf16 v[46:49], v[162:165], v[170:173], v[46:49]
	v_mfma_f32_16x16x32_bf16 v[34:37], v[154:157], v[178:181], v[34:37]
	v_mfma_f32_16x16x32_bf16 v[30:33], v[162:165], v[178:181], v[30:33]
	v_mfma_f32_16x16x32_bf16 v[22:25], v[154:157], v[186:189], v[22:25]
	v_mfma_f32_16x16x32_bf16 v[14:17], v[162:165], v[186:189], v[14:17]
	v_mfma_f32_16x16x32_bf16 v[6:9], v[154:157], v[194:197], v[6:9]
	v_mfma_f32_16x16x32_bf16 v[2:5], v[162:165], v[194:197], v[2:5]
	v_mfma_f32_16x16x32_bf16 v[50:53], v[158:161], v[174:177], v[50:53]
	v_mfma_f32_16x16x32_bf16 v[46:49], v[166:169], v[174:177], v[46:49]
	v_mfma_f32_16x16x32_bf16 v[34:37], v[158:161], v[182:185], v[34:37]
	v_mfma_f32_16x16x32_bf16 v[30:33], v[166:169], v[182:185], v[30:33]
	v_mfma_f32_16x16x32_bf16 v[22:25], v[158:161], v[190:193], v[22:25]
	v_mfma_f32_16x16x32_bf16 v[14:17], v[166:169], v[190:193], v[14:17]
	v_mfma_f32_16x16x32_bf16 v[6:9], v[158:161], v[198:201], v[6:9]
	v_mfma_f32_16x16x32_bf16 v[2:5], v[166:169], v[198:201], v[2:5]
	s_setprio 0
	s_barrier
	s_add_i32 s2, s2, 2
	s_addk_i32 s3, 0x100
	s_cmp_gt_u32 s2, 41
	s_cbranch_scc0 .LBB0_1135
	s_andn2_b64 vcc, exec, s[4:5]
	s_cbranch_vccnz .LBB0_1123
	v_mov_b32_e32 v2, 0
	s_mov_b32 s20, s50
	s_mov_b32 s25, s51
	s_mov_b32 s30, s54
	s_mov_b32 s36, s53
	s_mov_b32 s49, s52
	v_mov_b32_e32 v3, v2
	v_mov_b32_e32 v4, v2
	v_mov_b32_e32 v5, v2
	v_mov_b32_e32 v6, v2
	v_mov_b32_e32 v7, v2
	v_mov_b32_e32 v8, v2
	v_mov_b32_e32 v9, v2
	v_mov_b32_e32 v14, v2
	v_mov_b32_e32 v15, v2
	v_mov_b32_e32 v16, v2
	v_mov_b32_e32 v17, v2
	v_mov_b32_e32 v22, v2
	v_mov_b32_e32 v23, v2
	v_mov_b32_e32 v24, v2
	v_mov_b32_e32 v25, v2
	v_mov_b32_e32 v30, v2
	v_mov_b32_e32 v31, v2
	v_mov_b32_e32 v32, v2
	v_mov_b32_e32 v33, v2
	v_mov_b32_e32 v34, v2
	v_mov_b32_e32 v35, v2
	v_mov_b32_e32 v36, v2
	v_mov_b32_e32 v37, v2
	v_mov_b32_e32 v46, v2
	v_mov_b32_e32 v47, v2
	v_mov_b32_e32 v48, v2
	v_mov_b32_e32 v49, v2
	v_mov_b32_e32 v50, v2
	v_mov_b32_e32 v51, v2
	v_mov_b32_e32 v52, v2
	v_mov_b32_e32 v53, v2
	v_mov_b32_e32 v10, v2
	v_mov_b32_e32 v11, v2
	v_mov_b32_e32 v12, v2
	v_mov_b32_e32 v13, v2
	v_mov_b32_e32 v18, v2
	v_mov_b32_e32 v19, v2
	v_mov_b32_e32 v20, v2
	v_mov_b32_e32 v21, v2
	v_mov_b32_e32 v26, v2
	v_mov_b32_e32 v27, v2
	v_mov_b32_e32 v28, v2
	v_mov_b32_e32 v29, v2
	v_mov_b32_e32 v38, v2
	v_mov_b32_e32 v39, v2
	v_mov_b32_e32 v40, v2
	v_mov_b32_e32 v41, v2
	v_mov_b32_e32 v42, v2
	v_mov_b32_e32 v43, v2
	v_mov_b32_e32 v44, v2
	v_mov_b32_e32 v45, v2
	v_mov_b32_e32 v54, v2
	v_mov_b32_e32 v55, v2
	v_mov_b32_e32 v56, v2
	v_mov_b32_e32 v57, v2
	v_mov_b32_e32 v58, v2
	v_mov_b32_e32 v59, v2
	v_mov_b32_e32 v60, v2
	v_mov_b32_e32 v61, v2
	v_mov_b32_e32 v62, v2
	v_mov_b32_e32 v63, v2
	v_mov_b32_e32 v64, v2
	v_mov_b32_e32 v65, v2
	v_mov_b32_e32 v66, v2
	v_mov_b32_e32 v67, v2
	v_mov_b32_e32 v68, v2
	v_mov_b32_e32 v69, v2
	v_mov_b32_e32 v70, v2
	v_mov_b32_e32 v71, v2
	v_mov_b32_e32 v72, v2
	v_mov_b32_e32 v73, v2
	v_mov_b32_e32 v78, v2
	v_mov_b32_e32 v79, v2
	v_mov_b32_e32 v80, v2
	v_mov_b32_e32 v81, v2
	v_mov_b32_e32 v82, v2
	v_mov_b32_e32 v83, v2
	v_mov_b32_e32 v84, v2
	v_mov_b32_e32 v85, v2
	v_mov_b32_e32 v94, v2
	v_mov_b32_e32 v95, v2
	v_mov_b32_e32 v96, v2
	v_mov_b32_e32 v97, v2
	v_mov_b32_e32 v98, v2
	v_mov_b32_e32 v99, v2
	v_mov_b32_e32 v100, v2
	v_mov_b32_e32 v101, v2
	v_mov_b32_e32 v110, v2
	v_mov_b32_e32 v111, v2
	v_mov_b32_e32 v112, v2
	v_mov_b32_e32 v113, v2
	v_mov_b32_e32 v114, v2
	v_mov_b32_e32 v115, v2
	v_mov_b32_e32 v116, v2
	v_mov_b32_e32 v117, v2
	v_mov_b32_e32 v74, v2
	v_mov_b32_e32 v75, v2
	v_mov_b32_e32 v76, v2
	v_mov_b32_e32 v77, v2
	v_mov_b32_e32 v86, v2
	v_mov_b32_e32 v87, v2
	v_mov_b32_e32 v88, v2
	v_mov_b32_e32 v89, v2
	v_mov_b32_e32 v90, v2
	v_mov_b32_e32 v91, v2
	v_mov_b32_e32 v92, v2
	v_mov_b32_e32 v93, v2
	v_mov_b32_e32 v102, v2
	v_mov_b32_e32 v103, v2
	v_mov_b32_e32 v104, v2
	v_mov_b32_e32 v105, v2
	v_mov_b32_e32 v106, v2
	v_mov_b32_e32 v107, v2
	v_mov_b32_e32 v108, v2
	v_mov_b32_e32 v109, v2
	v_mov_b32_e32 v118, v2
	v_mov_b32_e32 v119, v2
	v_mov_b32_e32 v120, v2
	v_mov_b32_e32 v121, v2
	v_mov_b32_e32 v122, v2
	v_mov_b32_e32 v123, v2
	v_mov_b32_e32 v124, v2
	v_mov_b32_e32 v125, v2
	v_mov_b32_e32 v126, v2
	v_mov_b32_e32 v127, v2
	v_mov_b32_e32 v128, v2
	v_mov_b32_e32 v129, v2
	s_branch .LBB0_1123
